# FFN-up fused epilogue: sigmoid pre-scale and +1 done as packed f32 ops (bit-exact)
# baseline (speedup 1.0000x reference)
; #define PG8_STAGE(bufoff, gbase, voff) do { _Pragma("unroll") for (int _i = 0; _i < 2; ++_i) \
;         __builtin_amdgcn_global_load_lds((const unsigned*)((const char*)(gbase) + (voff)[_i]), (LAS unsigned*)(lds + (bufoff) + ldsw + _i * 8192), 16, 0, 0); } while (0)
; #define PG8_LDA(dst, b, h) do { _Pragma("unroll") for (int m = 0; m < 4; ++m) _Pragma("unroll") for (int k = 0; k < 2; ++k) dst[m][k] = *(const LAS bf16x8*)(lds + PG8_SA(b, h) + aoff + m * 2048 + k * 1024); } while (0)
; #define PG8_LDB(dst, b, h) do { _Pragma("unroll") for (int n = 0; n < 2; ++n) _Pragma("unroll") for (int k = 0; k < 2; ++k) dst[n][k] = *(const LAS bf16x8*)(lds + PG8_SB(b, h) + boff + n * 2048 + k * 1024); } while (0)
; #define PG8_WAIT_V(n) asm volatile("s_waitcnt vmcnt(" #n ")" ::: "memory")
; #define PG8_WAIT_L(n) asm volatile("s_waitcnt lgkmcnt(" #n ")" ::: "memory")
; #define PG8_BAR __builtin_amdgcn_s_barrier()
; #define PG8_SCHED __builtin_amdgcn_sched_barrier(0)
; template <class F>
; DI void gemm_phase(const int tid, LAS unsigned char* lds, const bf16_t* Ap, int lda, const bf16_t* Bp, int ldb, int M, int N, int K, int G, int c, bool direct, const F& E) {
;     ...
;         for (int t = 0; t < nt; t += 2) {
;             const bool last = (t == nt - 2);
;             const char* a1 = cA + (size_t)(t + 1) * kstep;
;             const char* a2 = last ? nA : cA + (size_t)(t + 2) * kstep; const char* b2 = last ? nB : cB + (size_t)(t + 2) * kstep;
;             const char* a3 = a2 + kstep; const char* b3 = b2 + kstep;
;             PG8_LDB(B0, 0, 0); PG8_SCHED; PG8_LDA(At, 0, 0); PG8_STAGE(PG8_SA(1, 1), a1 + hsA, voffA);
;             PG8_WAIT_L(8); PG8_BAR; PG8_WAIT_L(0); PG8_MMA(0, 0, At, B0); PG8_BAR; PG8_SCHED;
;             PG8_LDB(B1, 0, 1); PG8_STAGE(PG8_SB(0, 0), b2, voffB);
;             PG8_BAR; PG8_WAIT_L(0); PG8_MMA(0, 1, At, B1); PG8_BAR;
;             PG8_LDA(At, 0, 1); PG8_STAGE(PG8_SA(0, 0), a2, voffA);
;             PG8_BAR; PG8_WAIT_L(0); PG8_MMA(1, 0, At, B0); PG8_BAR; PG8_SCHED;
;             PG8_STAGE(PG8_SB(0, 1), b2 + hsB, voffB);
;             PG8_WAIT_V(6); PG8_BAR; PG8_MMA(1, 1, At, B1); PG8_BAR;
;             PG8_LDB(B0, 1, 0); PG8_SCHED; PG8_LDA(At, 1, 0); PG8_STAGE(PG8_SA(0, 1), a2 + hsA, voffA);
;             PG8_WAIT_L(8); PG8_BAR; PG8_WAIT_L(0); PG8_MMA(0, 0, At, B0); PG8_BAR; PG8_SCHED;
.LBB0_657:
	s_add_i32 s81, s76, 2
	s_add_u32 s78, s74, 0x80
	s_addc_u32 s77, s75, 0
	s_add_i32 s82, 0, 0x10000
	v_add_u32_e32 v140, s82, v189
	ds_read_b128 v[128:131], v140
	ds_read_b128 v[132:135], v140 offset:1024
	ds_read_b128 v[136:139], v140 offset:2048
	ds_read_b128 v[140:143], v140 offset:3072
	s_cmp_eq_u32 s67, s76
	s_cselect_b32 s76, s0, s78
	s_cselect_b32 s77, s1, s77
	s_cselect_b32 s79, s5, s80
	s_cselect_b32 s78, s4, s71
	s_add_u32 s98, s78, 0x80
	s_addc_u32 s99, s79, 0
	s_add_u32 s100, s76, 0x80
	s_addc_u32 s101, s77, 0
	s_add_i32 m0, s28, 0xc000
	ds_read_b128 v[144:147], v197
	ds_read_b128 v[148:151], v197 offset:1024
	ds_read_b128 v[152:155], v197 offset:2048
	ds_read_b128 v[156:159], v197 offset:3072
	ds_read_b128 v[160:163], v197 offset:4096
	ds_read_b128 v[164:167], v197 offset:5120
	ds_read_b128 v[168:171], v197 offset:6144
	ds_read_b128 v[172:175], v197 offset:7168
	global_load_lds_dwordx4 v204, s[74:75]
	s_add_i32 m0, s28, 0xe000
	s_nop 0
	global_load_lds_dwordx4 v206, s[74:75]
	s_waitcnt lgkmcnt(8)
	s_barrier
	s_waitcnt lgkmcnt(0)
	s_waitcnt lgkmcnt(0)
	v_mfma_f32_16x16x32_bf16 v[124:127], v[128:131], v[144:147], v[124:127]
	v_mfma_f32_16x16x32_bf16 v[120:123], v[136:139], v[144:147], v[120:123]
	v_mfma_f32_16x16x32_bf16 v[116:119], v[128:131], v[152:155], v[116:119]
	v_mfma_f32_16x16x32_bf16 v[104:107], v[136:139], v[152:155], v[104:107]
	v_mfma_f32_16x16x32_bf16 v[100:103], v[128:131], v[160:163], v[100:103]
	v_mfma_f32_16x16x32_bf16 v[88:91], v[136:139], v[160:163], v[88:91]
	v_mfma_f32_16x16x32_bf16 v[84:87], v[128:131], v[168:171], v[84:87]
	v_mfma_f32_16x16x32_bf16 v[72:75], v[136:139], v[168:171], v[72:75]
	v_mfma_f32_16x16x32_bf16 v[124:127], v[132:135], v[148:151], v[124:127]
	v_mfma_f32_16x16x32_bf16 v[120:123], v[140:143], v[148:151], v[120:123]
	v_mfma_f32_16x16x32_bf16 v[116:119], v[132:135], v[156:159], v[116:119]
	v_mfma_f32_16x16x32_bf16 v[104:107], v[140:143], v[156:159], v[104:107]
	v_mfma_f32_16x16x32_bf16 v[100:103], v[132:135], v[164:167], v[100:103]
	v_mfma_f32_16x16x32_bf16 v[88:91], v[140:143], v[164:167], v[88:91]
	v_mfma_f32_16x16x32_bf16 v[84:87], v[132:135], v[172:175], v[84:87]
	v_mfma_f32_16x16x32_bf16 v[72:75], v[140:143], v[172:175], v[72:75]
	s_barrier
	s_add_i32 s82, s82, s27
	v_add_u32_e32 v180, s95, v189
	s_mov_b32 m0, s82
	ds_read_b128 v[208:211], v180
	ds_read_b128 v[212:215], v180 offset:1024
	ds_read_b128 v[216:219], v180 offset:2048
	ds_read_b128 v[220:223], v180 offset:3072
	global_load_lds_dwordx4 v178, s[78:79]
	s_add_i32 m0, s82, 0x2000
	s_nop 0
	global_load_lds_dwordx4 v186, s[78:79]
	s_barrier
	s_waitcnt lgkmcnt(0)
	s_waitcnt lgkmcnt(0)
	v_mfma_f32_16x16x32_bf16 v[112:115], v[208:211], v[144:147], v[112:115]
	v_mfma_f32_16x16x32_bf16 v[108:111], v[216:219], v[144:147], v[108:111]
	v_mfma_f32_16x16x32_bf16 v[96:99], v[208:211], v[152:155], v[96:99]
	v_mfma_f32_16x16x32_bf16 v[92:95], v[216:219], v[152:155], v[92:95]
	v_mfma_f32_16x16x32_bf16 v[80:83], v[208:211], v[160:163], v[80:83]
	v_mfma_f32_16x16x32_bf16 v[76:79], v[216:219], v[160:163], v[76:79]
	v_mfma_f32_16x16x32_bf16 v[68:71], v[208:211], v[168:171], v[68:71]
	v_mfma_f32_16x16x32_bf16 v[64:67], v[216:219], v[168:171], v[64:67]
	v_mfma_f32_16x16x32_bf16 v[112:115], v[212:215], v[148:151], v[112:115]
	v_mfma_f32_16x16x32_bf16 v[108:111], v[220:223], v[148:151], v[108:111]
	v_mfma_f32_16x16x32_bf16 v[96:99], v[212:215], v[156:159], v[96:99]
	v_mfma_f32_16x16x32_bf16 v[92:95], v[220:223], v[156:159], v[92:95]
	v_mfma_f32_16x16x32_bf16 v[80:83], v[212:215], v[164:167], v[80:83]
	v_mfma_f32_16x16x32_bf16 v[76:79], v[220:223], v[164:167], v[76:79]
	v_mfma_f32_16x16x32_bf16 v[68:71], v[212:215], v[172:175], v[68:71]
	v_mfma_f32_16x16x32_bf16 v[64:67], v[220:223], v[172:175], v[64:67]
	s_mov_b32 m0, s28
	s_barrier
	ds_read_b128 v[144:147], v197 offset:16384
	ds_read_b128 v[148:151], v197 offset:17408
	ds_read_b128 v[152:155], v197 offset:18432
	ds_read_b128 v[156:159], v197 offset:19456
	ds_read_b128 v[160:163], v197 offset:20480
	ds_read_b128 v[164:167], v197 offset:21504
	ds_read_b128 v[168:171], v197 offset:22528
	ds_read_b128 v[172:175], v197 offset:23552
	global_load_lds_dwordx4 v176, s[76:77]
	s_mov_b32 m0, s34
	s_nop 0
	global_load_lds_dwordx4 v184, s[76:77]
	s_barrier
	s_waitcnt lgkmcnt(0)
	s_waitcnt lgkmcnt(0)
	v_mfma_f32_16x16x32_bf16 v[60:63], v[128:131], v[144:147], v[60:63]
	v_mfma_f32_16x16x32_bf16 v[56:59], v[136:139], v[144:147], v[56:59]
	v_mfma_f32_16x16x32_bf16 v[52:55], v[128:131], v[152:155], v[52:55]
	v_mfma_f32_16x16x32_bf16 v[40:43], v[136:139], v[152:155], v[40:43]
	v_mfma_f32_16x16x32_bf16 v[36:39], v[128:131], v[160:163], v[36:39]
	v_mfma_f32_16x16x32_bf16 v[16:19], v[136:139], v[160:163], v[16:19]
	v_mfma_f32_16x16x32_bf16 v[12:15], v[128:131], v[168:171], v[12:15]
	v_mfma_f32_16x16x32_bf16 v[0:3], v[136:139], v[168:171], v[0:3]
	v_mfma_f32_16x16x32_bf16 v[60:63], v[132:135], v[148:151], v[60:63]
	v_mfma_f32_16x16x32_bf16 v[56:59], v[140:143], v[148:151], v[56:59]
	v_mfma_f32_16x16x32_bf16 v[52:55], v[132:135], v[156:159], v[52:55]
	v_mfma_f32_16x16x32_bf16 v[40:43], v[140:143], v[156:159], v[40:43]
	v_mfma_f32_16x16x32_bf16 v[36:39], v[132:135], v[164:167], v[36:39]
	v_mfma_f32_16x16x32_bf16 v[16:19], v[140:143], v[164:167], v[16:19]
	v_mfma_f32_16x16x32_bf16 v[12:15], v[132:135], v[172:175], v[12:15]
	v_mfma_f32_16x16x32_bf16 v[0:3], v[140:143], v[172:175], v[0:3]
	s_barrier
	s_add_u32 s78, s78, s46
	s_addc_u32 s79, s79, 0
	s_add_u32 vcc_lo, s78, 0x80
	s_addc_u32 vcc_hi, s79, 0
	s_add_i32 s82, s95, s27
	s_mov_b32 m0, s82
	s_nop 0
	global_load_lds_dwordx4 v178, s[78:79]
	s_add_i32 m0, s82, 0x2000
	s_nop 0
	global_load_lds_dwordx4 v186, s[78:79]
	s_waitcnt vmcnt(6)
	s_barrier
; #define PG8_STAGE(bufoff, gbase, voff) do { _Pragma("unroll") for (int _i = 0; _i < 2; ++_i) \
;         __builtin_amdgcn_global_load_lds((const unsigned*)((const char*)(gbase) + (voff)[_i]), (LAS unsigned*)(lds + (bufoff) + ldsw + _i * 8192), 16, 0, 0); } while (0)
; #define PG8_LDA(dst, b, h) do { _Pragma("unroll") for (int m = 0; m < 4; ++m) _Pragma("unroll") for (int k = 0; k < 2; ++k) dst[m][k] = *(const LAS bf16x8*)(lds + PG8_SA(b, h) + aoff + m * 2048 + k * 1024); } while (0)
; #define PG8_LDB(dst, b, h) do { _Pragma("unroll") for (int n = 0; n < 2; ++n) _Pragma("unroll") for (int k = 0; k < 2; ++k) dst[n][k] = *(const LAS bf16x8*)(lds + PG8_SB(b, h) + boff + n * 2048 + k * 1024); } while (0)
; #define PG8_MMA(ai, bj, At, Bt) do { __builtin_amdgcn_s_setprio(1); _Pragma("unroll") for (int m = 0; m < 4; ++m) _Pragma("unroll") for (int n = 0; n < 2; ++n) _Pragma("unroll") for (int k = 0; k < 2; ++k) \
;         acc[ai][bj][m][n] = __builtin_amdgcn_mfma_f32_16x16x32_bf16(Bt[n][k], At[m][k], acc[ai][bj][m][n], 0, 0, 0); __builtin_amdgcn_s_setprio(0); } while (0)
; #define PG8_WAIT_V(n) asm volatile("s_waitcnt vmcnt(" #n ")" ::: "memory")
; #define PG8_WAIT_L(n) asm volatile("s_waitcnt lgkmcnt(" #n ")" ::: "memory")
; #define PG8_BAR __builtin_amdgcn_s_barrier()
; #define PG8_SCHED __builtin_amdgcn_sched_barrier(0)
; template <class F>
; DI void gemm_phase(const int tid, LAS unsigned char* lds, const bf16_t* Ap, int lda, const bf16_t* Bp, int ldb, int M, int N, int K, int G, int c, bool direct, const F& E) {
;     ...
;             PG8_WAIT_V(6); PG8_BAR; PG8_MMA(1, 1, At, B1); PG8_BAR;
;             PG8_LDB(B0, 1, 0); PG8_SCHED; PG8_LDA(At, 1, 0); PG8_STAGE(PG8_SA(0, 1), a2 + hsA, voffA);
;             PG8_WAIT_L(8); PG8_BAR; PG8_WAIT_L(0); PG8_MMA(0, 0, At, B0); PG8_BAR; PG8_SCHED;
;             PG8_LDB(B1, 1, 1); PG8_STAGE(PG8_SB(1, 0), b3, voffB);
;             PG8_BAR; PG8_WAIT_L(0); PG8_MMA(0, 1, At, B1); PG8_BAR;
;             PG8_LDA(At, 1, 1); PG8_STAGE(PG8_SA(1, 0), a3, voffA);
	v_mfma_f32_16x16x32_bf16 v[48:51], v[208:211], v[144:147], v[48:51]
	v_mfma_f32_16x16x32_bf16 v[44:47], v[216:219], v[144:147], v[44:47]
	v_mfma_f32_16x16x32_bf16 v[24:27], v[208:211], v[152:155], v[24:27]
	v_mfma_f32_16x16x32_bf16 v[20:23], v[216:219], v[152:155], v[20:23]
	v_mfma_f32_16x16x32_bf16 v[28:31], v[208:211], v[160:163], v[28:31]
	v_mfma_f32_16x16x32_bf16 v[32:35], v[216:219], v[160:163], v[32:35]
	v_mfma_f32_16x16x32_bf16 v[8:11], v[208:211], v[168:171], v[8:11]
	v_mfma_f32_16x16x32_bf16 v[4:7], v[216:219], v[168:171], v[4:7]
	v_mfma_f32_16x16x32_bf16 v[48:51], v[212:215], v[148:151], v[48:51]
	v_mfma_f32_16x16x32_bf16 v[44:47], v[220:223], v[148:151], v[44:47]
	v_mfma_f32_16x16x32_bf16 v[24:27], v[212:215], v[156:159], v[24:27]
	v_mfma_f32_16x16x32_bf16 v[20:23], v[220:223], v[156:159], v[20:23]
	v_mfma_f32_16x16x32_bf16 v[28:31], v[212:215], v[164:167], v[28:31]
	v_mfma_f32_16x16x32_bf16 v[32:35], v[220:223], v[164:167], v[32:35]
	v_mfma_f32_16x16x32_bf16 v[8:11], v[212:215], v[172:175], v[8:11]
	v_mfma_f32_16x16x32_bf16 v[4:7], v[220:223], v[172:175], v[4:7]
	s_add_i32 s78, 0, 0x18000
	v_add_u32_e32 v140, s78, v189
	s_barrier
	ds_read_b128 v[128:131], v140
	ds_read_b128 v[132:135], v140 offset:1024
	ds_read_b128 v[136:139], v140 offset:2048
	ds_read_b128 v[140:143], v140 offset:3072
	s_add_u32 s76, s76, s24
	s_addc_u32 s77, s77, 0
	s_mov_b32 m0, s60
	ds_read_b128 v[144:147], v197 offset:32768
	ds_read_b128 v[148:151], v197 offset:33792
	ds_read_b128 v[152:155], v197 offset:34816
	ds_read_b128 v[156:159], v197 offset:35840
	ds_read_b128 v[160:163], v197 offset:36864
	ds_read_b128 v[164:167], v197 offset:37888
	ds_read_b128 v[168:171], v197 offset:38912
	ds_read_b128 v[172:175], v197 offset:39936
	global_load_lds_dwordx4 v176, s[76:77]
	s_mov_b32 m0, s61
	s_nop 0
	global_load_lds_dwordx4 v184, s[76:77]
	s_waitcnt lgkmcnt(8)
	s_barrier
	s_waitcnt lgkmcnt(0)
	s_waitcnt lgkmcnt(0)
	v_mfma_f32_16x16x32_bf16 v[124:127], v[128:131], v[144:147], v[124:127]
	v_mfma_f32_16x16x32_bf16 v[120:123], v[136:139], v[144:147], v[120:123]
	v_mfma_f32_16x16x32_bf16 v[116:119], v[128:131], v[152:155], v[116:119]
	v_mfma_f32_16x16x32_bf16 v[104:107], v[136:139], v[152:155], v[104:107]
	v_mfma_f32_16x16x32_bf16 v[100:103], v[128:131], v[160:163], v[100:103]
	v_mfma_f32_16x16x32_bf16 v[88:91], v[136:139], v[160:163], v[88:91]
	v_mfma_f32_16x16x32_bf16 v[84:87], v[128:131], v[168:171], v[84:87]
	v_mfma_f32_16x16x32_bf16 v[72:75], v[136:139], v[168:171], v[72:75]
	v_mfma_f32_16x16x32_bf16 v[124:127], v[132:135], v[148:151], v[124:127]
	v_mfma_f32_16x16x32_bf16 v[120:123], v[140:143], v[148:151], v[120:123]
	v_mfma_f32_16x16x32_bf16 v[116:119], v[132:135], v[156:159], v[116:119]
	v_mfma_f32_16x16x32_bf16 v[104:107], v[140:143], v[156:159], v[104:107]
	v_mfma_f32_16x16x32_bf16 v[100:103], v[132:135], v[164:167], v[100:103]
	v_mfma_f32_16x16x32_bf16 v[88:91], v[140:143], v[164:167], v[88:91]
	v_mfma_f32_16x16x32_bf16 v[84:87], v[132:135], v[172:175], v[84:87]
	v_mfma_f32_16x16x32_bf16 v[72:75], v[140:143], v[172:175], v[72:75]
	s_barrier
	s_add_i32 s76, 0, 0x1c000
	s_add_i32 s77, s78, s27
	v_add_u32_e32 v180, s76, v189
	s_mov_b32 m0, s77
	ds_read_b128 v[208:211], v180
	ds_read_b128 v[212:215], v180 offset:1024
	ds_read_b128 v[216:219], v180 offset:2048
	ds_read_b128 v[220:223], v180 offset:3072
	global_load_lds_dwordx4 v178, s[98:99]
	s_add_i32 m0, s77, 0x2000
	s_nop 0
	global_load_lds_dwordx4 v186, s[98:99]
	s_barrier
	s_waitcnt lgkmcnt(0)
	s_waitcnt lgkmcnt(0)
	v_mfma_f32_16x16x32_bf16 v[112:115], v[208:211], v[144:147], v[112:115]
	v_mfma_f32_16x16x32_bf16 v[108:111], v[216:219], v[144:147], v[108:111]
	v_mfma_f32_16x16x32_bf16 v[96:99], v[208:211], v[152:155], v[96:99]
	v_mfma_f32_16x16x32_bf16 v[92:95], v[216:219], v[152:155], v[92:95]
	v_mfma_f32_16x16x32_bf16 v[80:83], v[208:211], v[160:163], v[80:83]
	v_mfma_f32_16x16x32_bf16 v[76:79], v[216:219], v[160:163], v[76:79]
	v_mfma_f32_16x16x32_bf16 v[68:71], v[208:211], v[168:171], v[68:71]
	v_mfma_f32_16x16x32_bf16 v[64:67], v[216:219], v[168:171], v[64:67]
	v_mfma_f32_16x16x32_bf16 v[112:115], v[212:215], v[148:151], v[112:115]
	v_mfma_f32_16x16x32_bf16 v[108:111], v[220:223], v[148:151], v[108:111]
	v_mfma_f32_16x16x32_bf16 v[96:99], v[212:215], v[156:159], v[96:99]
	v_mfma_f32_16x16x32_bf16 v[92:95], v[220:223], v[156:159], v[92:95]
	v_mfma_f32_16x16x32_bf16 v[80:83], v[212:215], v[164:167], v[80:83]
	v_mfma_f32_16x16x32_bf16 v[76:79], v[220:223], v[164:167], v[76:79]
	v_mfma_f32_16x16x32_bf16 v[68:71], v[212:215], v[172:175], v[68:71]
	v_mfma_f32_16x16x32_bf16 v[64:67], v[220:223], v[172:175], v[64:67]
	s_mov_b32 m0, s62
	s_barrier
	ds_read_b128 v[144:147], v197 offset:49152
	ds_read_b128 v[148:151], v197 offset:50176
	ds_read_b128 v[152:155], v197 offset:51200
	ds_read_b128 v[156:159], v197 offset:52224
	ds_read_b128 v[160:163], v197 offset:53248
	ds_read_b128 v[164:167], v197 offset:54272
	ds_read_b128 v[168:171], v197 offset:55296
	ds_read_b128 v[172:175], v197 offset:56320
	global_load_lds_dwordx4 v176, s[100:101]
	s_mov_b32 m0, s63
	s_nop 0
	global_load_lds_dwordx4 v184, s[100:101]
	s_barrier
; #define PG8_STAGE(bufoff, gbase, voff) do { _Pragma("unroll") for (int _i = 0; _i < 2; ++_i) \
;         __builtin_amdgcn_global_load_lds((const unsigned*)((const char*)(gbase) + (voff)[_i]), (LAS unsigned*)(lds + (bufoff) + ldsw + _i * 8192), 16, 0, 0); } while (0)
; #define PG8_LDA(dst, b, h) do { _Pragma("unroll") for (int m = 0; m < 4; ++m) _Pragma("unroll") for (int k = 0; k < 2; ++k) dst[m][k] = *(const LAS bf16x8*)(lds + PG8_SA(b, h) + aoff + m * 2048 + k * 1024); } while (0)
; #define PG8_LDB(dst, b, h) do { _Pragma("unroll") for (int n = 0; n < 2; ++n) _Pragma("unroll") for (int k = 0; k < 2; ++k) dst[n][k] = *(const LAS bf16x8*)(lds + PG8_SB(b, h) + boff + n * 2048 + k * 1024); } while (0)
; #define PG8_WAIT_V(n) asm volatile("s_waitcnt vmcnt(" #n ")" ::: "memory")
; #define PG8_WAIT_L(n) asm volatile("s_waitcnt lgkmcnt(" #n ")" ::: "memory")
; template <class F>
; DI void gemm_phase(const int tid, LAS unsigned char* lds, const bf16_t* Ap, int lda, const bf16_t* Bp, int ldb, int M, int N, int K, int G, int c, bool direct, const F& E) {
;     ...
;             PG8_WAIT_V(6); PG8_BAR; PG8_MMA(1, 1, At, B1); PG8_BAR;
;             PG8_LDB(B0, 1, 0); PG8_SCHED; PG8_LDA(At, 1, 0); PG8_STAGE(PG8_SA(0, 1), a2 + hsA, voffA);
;             PG8_WAIT_L(8); PG8_BAR; PG8_WAIT_L(0); PG8_MMA(0, 0, At, B0); PG8_BAR; PG8_SCHED;
;             PG8_LDB(B1, 1, 1); PG8_STAGE(PG8_SB(1, 0), b3, voffB);
;             PG8_BAR; PG8_WAIT_L(0); PG8_MMA(0, 1, At, B1); PG8_BAR;
;             PG8_LDA(At, 1, 1); PG8_STAGE(PG8_SA(1, 0), a3, voffA);
;             PG8_BAR; PG8_WAIT_L(0); PG8_MMA(1, 0, At, B0); PG8_BAR; PG8_SCHED;
;             PG8_STAGE(PG8_SB(1, 1), b3 + hsB, voffB);
;             PG8_WAIT_V(6); PG8_BAR; PG8_MMA(1, 1, At, B1); PG8_BAR;
; DI void Epi::fused(const f32x4 (&acc)[2][2][4][2], int pm, int pn, int wr, int wc, int fr, int fq) const {
;     ...
;     for (int bj = 0; bj < 2; ++bj) {
;         const int ncol = pn * 256 + bj * 128 + wc * 32 + 8 * fq, j0 = (ncol >> 3) * 4;
;         const f32x4 wa0 = *(const f32x4*)(E.cf0 + j0), wa1 = *(const f32x4*)(E.cf0 + FF2 + j0), wa2 = *(const f32x4*)(E.cf0 + 2 * FF2 + j0);
;         const f32x4 wb0 = *(const f32x4*)(E.cf0 + FFH + j0), wb1 = *(const f32x4*)(E.cf0 + FF2 + FFH + j0), wb2 = *(const f32x4*)(E.cf0 + 2 * FF2 + FFH + j0);
;         const f32x4 ba = *(const f32x4*)(E.cf1 + j0), bb = *(const f32x4*)(E.cf1 + FFH + j0);
	s_waitcnt lgkmcnt(0)
	s_waitcnt lgkmcnt(0)
	v_mfma_f32_16x16x32_bf16 v[60:63], v[128:131], v[144:147], v[60:63]
	v_mfma_f32_16x16x32_bf16 v[56:59], v[136:139], v[144:147], v[56:59]
	v_mfma_f32_16x16x32_bf16 v[52:55], v[128:131], v[152:155], v[52:55]
	v_mfma_f32_16x16x32_bf16 v[40:43], v[136:139], v[152:155], v[40:43]
	v_mfma_f32_16x16x32_bf16 v[36:39], v[128:131], v[160:163], v[36:39]
	v_mfma_f32_16x16x32_bf16 v[16:19], v[136:139], v[160:163], v[16:19]
	v_mfma_f32_16x16x32_bf16 v[12:15], v[128:131], v[168:171], v[12:15]
	v_mfma_f32_16x16x32_bf16 v[0:3], v[136:139], v[168:171], v[0:3]
	v_mfma_f32_16x16x32_bf16 v[60:63], v[132:135], v[148:151], v[60:63]
	v_mfma_f32_16x16x32_bf16 v[56:59], v[140:143], v[148:151], v[56:59]
	v_mfma_f32_16x16x32_bf16 v[52:55], v[132:135], v[156:159], v[52:55]
	v_mfma_f32_16x16x32_bf16 v[40:43], v[140:143], v[156:159], v[40:43]
	v_mfma_f32_16x16x32_bf16 v[36:39], v[132:135], v[164:167], v[36:39]
	v_mfma_f32_16x16x32_bf16 v[16:19], v[140:143], v[164:167], v[16:19]
	v_mfma_f32_16x16x32_bf16 v[12:15], v[132:135], v[172:175], v[12:15]
	v_mfma_f32_16x16x32_bf16 v[0:3], v[140:143], v[172:175], v[0:3]
	s_barrier
	s_add_i32 s76, s76, s27
	s_mov_b32 m0, s76
	s_nop 0
	global_load_lds_dwordx4 v178, vcc
	s_add_i32 m0, s76, 0x2000
	s_nop 0
	global_load_lds_dwordx4 v186, vcc
	s_waitcnt vmcnt(6)
	s_barrier
	v_mfma_f32_16x16x32_bf16 v[48:51], v[208:211], v[144:147], v[48:51]
	v_mfma_f32_16x16x32_bf16 v[44:47], v[216:219], v[144:147], v[44:47]
	v_mfma_f32_16x16x32_bf16 v[24:27], v[208:211], v[152:155], v[24:27]
	v_mfma_f32_16x16x32_bf16 v[20:23], v[216:219], v[152:155], v[20:23]
	v_mfma_f32_16x16x32_bf16 v[28:31], v[208:211], v[160:163], v[28:31]
	v_mfma_f32_16x16x32_bf16 v[32:35], v[216:219], v[160:163], v[32:35]
	v_mfma_f32_16x16x32_bf16 v[8:11], v[208:211], v[168:171], v[8:11]
	v_mfma_f32_16x16x32_bf16 v[4:7], v[216:219], v[168:171], v[4:7]
	v_mfma_f32_16x16x32_bf16 v[48:51], v[212:215], v[148:151], v[48:51]
	v_mfma_f32_16x16x32_bf16 v[44:47], v[220:223], v[148:151], v[44:47]
	v_mfma_f32_16x16x32_bf16 v[24:27], v[212:215], v[156:159], v[24:27]
	v_mfma_f32_16x16x32_bf16 v[20:23], v[220:223], v[156:159], v[20:23]
	v_mfma_f32_16x16x32_bf16 v[28:31], v[212:215], v[164:167], v[28:31]
	v_mfma_f32_16x16x32_bf16 v[32:35], v[220:223], v[164:167], v[32:35]
	v_mfma_f32_16x16x32_bf16 v[8:11], v[212:215], v[172:175], v[8:11]
	v_mfma_f32_16x16x32_bf16 v[4:7], v[220:223], v[172:175], v[4:7]
	s_add_u32 s74, s74, 0x100
	s_addc_u32 s75, s75, 0
	s_add_u32 s71, s71, 0x100
	s_addc_u32 s80, s80, 0
	s_cmp_ge_u32 s81, s26
	s_mov_b32 s76, s81
	s_barrier
	s_cbranch_scc0 .LBB0_657
	s_mov_b64 s[76:77], -1
	s_mov_b64 s[74:75], 0
	s_cmp_lt_i32 s92, 3
	s_mov_b64 s[78:79], 0
	s_cbranch_scc1 .LBB0_688
	s_cmp_gt_i32 s92, 6
	s_mov_b64 s[78:79], -1
	s_cbranch_scc0 .LBB0_685
	s_mov_b32 s98, 0xbfb8aa3b
	s_mov_b32 s99, 0xbfb8aa3b
	s_mov_b32 s100, 1.0
	s_mov_b32 s101, 1.0
	v_lshl_or_b32 v240, s70, 8, v194
	v_mov_b32_e32 v241, 0
	s_lshl_b32 s71, s36, 8
	v_readlane_b32 s76, v255, 16
	s_nop 3
	s_add_i32 s71, s71, s76
	v_or_b32_e32 v199, s71, v188
	v_lshlrev_b32_e32 v238, 1, v240
	v_mov_b32_e32 v239, 0
	v_lshl_add_u64 v[136:137], s[22:23], 0, v[238:239]
	global_load_dwordx4 v[136:139], v[136:137], off
	v_readlane_b32 s76, v254, 54
	v_readlane_b32 s77, v254, 55
	s_nop 1
	v_lshl_add_u64 v[140:141], s[76:77], 0, v[238:239]
	global_load_dwordx4 v[140:143], v[140:141], off
	v_readlane_b32 s76, v254, 56
	v_readlane_b32 s77, v254, 57
	s_nop 1
	v_lshl_add_u64 v[152:153], s[76:77], 0, v[238:239]
	global_load_dwordx4 v[152:155], v[152:153], off
	v_readlane_b32 s76, v255, 4
	v_readlane_b32 s77, v255, 5
	s_nop 1
	v_lshl_add_u64 v[128:129], s[76:77], 0, v[238:239]
	global_load_dwordx4 v[128:131], v[128:129], off
	v_readlane_b32 s76, v255, 6
	v_readlane_b32 s77, v255, 7
	s_nop 1
	v_lshl_add_u64 v[132:133], s[76:77], 0, v[238:239]
	global_load_dwordx4 v[132:135], v[132:133], off
	v_readlane_b32 s76, v255, 8
	v_readlane_b32 s77, v255, 9
	s_nop 1
	v_lshl_add_u64 v[144:145], s[76:77], 0, v[238:239]
	global_load_dwordx4 v[144:147], v[144:145], off
	v_readlane_b32 s76, v254, 49
	v_readlane_b32 s77, v254, 50
	s_nop 1
	v_lshl_add_u64 v[156:157], s[76:77], 0, v[238:239]
	global_load_dwordx4 v[156:159], v[156:157], off
	v_lshl_add_u64 v[148:149], s[72:73], 0, v[238:239]
	global_load_dwordx4 v[148:151], v[148:149], off
	v_mov_b32_e32 v228, v199
	v_mov_b64_e32 v[224:225], s[12:13]
	s_movk_i32 s80, 0x1600
	v_mad_i64_i32 v[224:225], s[78:79], v228, s80, v[224:225]
	v_mov_b32_e32 v228, v240
	v_mov_b32_e32 v229, 0
	v_lshl_add_u64 v[224:225], v[228:229], 0, v[224:225]
	s_waitcnt vmcnt(0)
; DI float silu_fast(float x) { return x * __builtin_amdgcn_rcpf(1.f + __expf(-x)); }
; template <int CTRL> DI float dppf(float v) { return __builtin_bit_cast(float, __builtin_amdgcn_update_dpp(0, __builtin_bit_cast(int, v), CTRL, 0xf, 0xf, true)); }
; DI void Epi::fused(const f32x4 (&acc)[2][2][4][2], int pm, int pn, int wr, int wc, int fr, int fq) const {
;     ...
;             for (int m = 0; m < 4; ++m) {
;                 const f32x4 ca = acc[ai][bj][m][0], cb = acc[ai][bj][m][1];
;                 const int row = pm * 256 + ai * 128 + wr * 64 + m * 16 + fr;
;                 float o[4];
; #pragma unroll
;                 for (int e = 0; e < 4; ++e) {
;                     const float a1 = dppf<0x111>(ca[e]) + dppf<0x10F>(pa[e]), a2 = dppf<0x112>(ca[e]) + dppf<0x10E>(pa[e]);
;                     const float b1 = dppf<0x111>(cb[e]) + dppf<0x10F>(pb[e]), b2 = dppf<0x112>(cb[e]) + dppf<0x10E>(pb[e]);
;                     const float ya = fmaf(wa0[e], a2, fmaf(wa1[e], a1, fmaf(wa2[e], ca[e], ba[e])));
;                     const float yb = fmaf(wb0[e], b2, fmaf(wb1[e], b1, fmaf(wb2[e], cb[e], bb[e])));
;                     o[e] = silu_fast(ya) * yb; }
;                 if (m > 0 || fr >= 2) { u32x2 w; w.x = pk2(o[0], o[1]); w.y = pk2(o[2], o[3]); *(u32x2*)(E.d0 + (size_t)row * FFH + j0) = w; }
;                 if ((m == 0 && fr < 2) || (m == 3 && fr >= 14)) { float* hb = E.f0 + ((size_t)(row >> 6) * 4 + (m == 0 ? fr : fr - 12)) * FF2 + ncol; *(f32x4*)hb = ca; *(f32x4*)(hb + 4) = cb; }
;                 pa = ca; pb = cb;
	v_fma_f32 v160, v152, v124, v156
	v_fma_f32 v161, v153, v125, v157
	v_fma_f32 v162, v154, v126, v158
	v_fma_f32 v163, v155, v127, v159
	v_fma_f32 v164, v144, v120, v148
	v_fma_f32 v165, v145, v121, v149
	v_fma_f32 v166, v146, v122, v150
	v_fma_f32 v167, v147, v123, v151
	v_fmac_f32_dpp v160, v124, v140 row_shr:1 row_mask:0xf bank_mask:0xf
	v_fmac_f32_dpp v161, v125, v141 row_shr:1 row_mask:0xf bank_mask:0xf
	v_fmac_f32_dpp v162, v126, v142 row_shr:1 row_mask:0xf bank_mask:0xf
	v_fmac_f32_dpp v163, v127, v143 row_shr:1 row_mask:0xf bank_mask:0xf
	v_fmac_f32_dpp v164, v120, v132 row_shr:1 row_mask:0xf bank_mask:0xf
	v_fmac_f32_dpp v165, v121, v133 row_shr:1 row_mask:0xf bank_mask:0xf
	v_fmac_f32_dpp v166, v122, v134 row_shr:1 row_mask:0xf bank_mask:0xf
	v_fmac_f32_dpp v167, v123, v135 row_shr:1 row_mask:0xf bank_mask:0xf
	v_fmac_f32_dpp v160, v124, v136 row_shr:2 row_mask:0xf bank_mask:0xf
	v_fmac_f32_dpp v161, v125, v137 row_shr:2 row_mask:0xf bank_mask:0xf
	v_fmac_f32_dpp v162, v126, v138 row_shr:2 row_mask:0xf bank_mask:0xf
	v_fmac_f32_dpp v163, v127, v139 row_shr:2 row_mask:0xf bank_mask:0xf
	v_fmac_f32_dpp v164, v120, v128 row_shr:2 row_mask:0xf bank_mask:0xf
	v_fmac_f32_dpp v165, v121, v129 row_shr:2 row_mask:0xf bank_mask:0xf
	v_fmac_f32_dpp v166, v122, v130 row_shr:2 row_mask:0xf bank_mask:0xf
	v_fmac_f32_dpp v167, v123, v131 row_shr:2 row_mask:0xf bank_mask:0xf
	v_pk_mul_f32 v[168:169], v[160:161], s[98:99]
	v_pk_mul_f32 v[170:171], v[162:163], s[98:99]
	v_exp_f32_e32 v168, v168
	v_exp_f32_e32 v169, v169
	v_exp_f32_e32 v170, v170
	v_exp_f32_e32 v171, v171
	v_pk_add_f32 v[168:169], v[168:169], s[100:101]
	v_pk_add_f32 v[170:171], v[170:171], s[100:101]
	v_rcp_f32_e32 v168, v168
	v_rcp_f32_e32 v169, v169
	v_rcp_f32_e32 v170, v170
	v_rcp_f32_e32 v171, v171
	v_mov_b64_e32 v[174:175], v[224:225]
	v_mul_f32_e32 v160, v160, v168
	v_mul_f32_e32 v161, v161, v169
	v_mul_f32_e32 v162, v162, v170
	v_mul_f32_e32 v163, v163, v171
	v_mul_f32_e32 v160, v164, v160
	v_mul_f32_e32 v161, v165, v161
	v_mul_f32_e32 v162, v166, v162
	v_mul_f32_e32 v163, v167, v163
	v_cvt_pk_bf16_f32 v172, v160, v161
	v_cvt_pk_bf16_f32 v173, v162, v163
	s_and_saveexec_b64 s[76:77], s[38:39]
	global_store_dwordx2 v[174:175], v[172:173], off
	s_or_b64 exec, exec, s[76:77]
	s_ashr_i32 s80, s71, 6
	s_lshl_b32 s80, s80, 2
	v_add_u32_e32 v226, s80, v188
	v_mov_b64_e32 v[174:175], s[8:9]
	s_movk_i32 s80, 0x5800
	v_mad_i64_i32 v[174:175], s[78:79], v226, s80, v[174:175]
	v_lshl_add_u64 v[174:175], v[228:229], 2, v[174:175]
	s_and_saveexec_b64 s[76:77], s[40:41]
	global_store_dwordx4 v[174:175], v[124:127], off
	global_store_dwordx4 v[174:175], v[120:123], off offset:16
	s_or_b64 exec, exec, s[76:77]
	v_fma_f32 v208, v152, v116, v156
	v_fma_f32 v209, v153, v117, v157
	v_fma_f32 v210, v154, v118, v158
	v_fma_f32 v211, v155, v119, v159
	v_fma_f32 v212, v144, v104, v148
	v_fma_f32 v213, v145, v105, v149
	v_fma_f32 v214, v146, v106, v150
	v_fma_f32 v215, v147, v107, v151
	v_fmac_f32_dpp v208, v116, v140 row_shr:1 row_mask:0xf bank_mask:0xf
	v_fmac_f32_dpp v209, v117, v141 row_shr:1 row_mask:0xf bank_mask:0xf
	v_fmac_f32_dpp v210, v118, v142 row_shr:1 row_mask:0xf bank_mask:0xf
	v_fmac_f32_dpp v211, v119, v143 row_shr:1 row_mask:0xf bank_mask:0xf
	v_fmac_f32_dpp v212, v104, v132 row_shr:1 row_mask:0xf bank_mask:0xf
	v_fmac_f32_dpp v213, v105, v133 row_shr:1 row_mask:0xf bank_mask:0xf
	v_fmac_f32_dpp v214, v106, v134 row_shr:1 row_mask:0xf bank_mask:0xf
	v_fmac_f32_dpp v215, v107, v135 row_shr:1 row_mask:0xf bank_mask:0xf
	v_fmac_f32_dpp v208, v124, v140 row_shl:15 row_mask:0xf bank_mask:0xf
	v_fmac_f32_dpp v209, v125, v141 row_shl:15 row_mask:0xf bank_mask:0xf
	v_fmac_f32_dpp v210, v126, v142 row_shl:15 row_mask:0xf bank_mask:0xf
	v_fmac_f32_dpp v211, v127, v143 row_shl:15 row_mask:0xf bank_mask:0xf
	v_fmac_f32_dpp v212, v120, v132 row_shl:15 row_mask:0xf bank_mask:0xf
	v_fmac_f32_dpp v213, v121, v133 row_shl:15 row_mask:0xf bank_mask:0xf
	v_fmac_f32_dpp v214, v122, v134 row_shl:15 row_mask:0xf bank_mask:0xf
	v_fmac_f32_dpp v215, v123, v135 row_shl:15 row_mask:0xf bank_mask:0xf
	v_fmac_f32_dpp v208, v116, v136 row_shr:2 row_mask:0xf bank_mask:0xf
	v_fmac_f32_dpp v209, v117, v137 row_shr:2 row_mask:0xf bank_mask:0xf
	v_fmac_f32_dpp v210, v118, v138 row_shr:2 row_mask:0xf bank_mask:0xf
	v_fmac_f32_dpp v211, v119, v139 row_shr:2 row_mask:0xf bank_mask:0xf
	v_fmac_f32_dpp v212, v104, v128 row_shr:2 row_mask:0xf bank_mask:0xf
	v_fmac_f32_dpp v213, v105, v129 row_shr:2 row_mask:0xf bank_mask:0xf
	v_fmac_f32_dpp v214, v106, v130 row_shr:2 row_mask:0xf bank_mask:0xf
	v_fmac_f32_dpp v215, v107, v131 row_shr:2 row_mask:0xf bank_mask:0xf
	v_fmac_f32_dpp v208, v124, v136 row_shl:14 row_mask:0xf bank_mask:0xf
	v_fmac_f32_dpp v209, v125, v137 row_shl:14 row_mask:0xf bank_mask:0xf
	v_fmac_f32_dpp v210, v126, v138 row_shl:14 row_mask:0xf bank_mask:0xf
	v_fmac_f32_dpp v211, v127, v139 row_shl:14 row_mask:0xf bank_mask:0xf
	v_fmac_f32_dpp v212, v120, v128 row_shl:14 row_mask:0xf bank_mask:0xf
	v_fmac_f32_dpp v213, v121, v129 row_shl:14 row_mask:0xf bank_mask:0xf
	v_fmac_f32_dpp v214, v122, v130 row_shl:14 row_mask:0xf bank_mask:0xf
	v_fmac_f32_dpp v215, v123, v131 row_shl:14 row_mask:0xf bank_mask:0xf
	v_pk_mul_f32 v[216:217], v[208:209], s[98:99]
	v_pk_mul_f32 v[218:219], v[210:211], s[98:99]
	v_exp_f32_e32 v216, v216
	v_exp_f32_e32 v217, v217
	v_exp_f32_e32 v218, v218
	v_exp_f32_e32 v219, v219
	v_pk_add_f32 v[216:217], v[216:217], s[100:101]
	v_pk_add_f32 v[218:219], v[218:219], s[100:101]
	v_rcp_f32_e32 v216, v216
	v_rcp_f32_e32 v217, v217
	v_rcp_f32_e32 v218, v218
	v_rcp_f32_e32 v219, v219
; DI float silu_fast(float x) { return x * __builtin_amdgcn_rcpf(1.f + __expf(-x)); }
; template <int CTRL> DI float dppf(float v) { return __builtin_bit_cast(float, __builtin_amdgcn_update_dpp(0, __builtin_bit_cast(int, v), CTRL, 0xf, 0xf, true)); }
; DI void Epi::fused(const f32x4 (&acc)[2][2][4][2], int pm, int pn, int wr, int wc, int fr, int fq) const {
;     ...
;             for (int m = 0; m < 4; ++m) {
;                 const f32x4 ca = acc[ai][bj][m][0], cb = acc[ai][bj][m][1];
;                 const int row = pm * 256 + ai * 128 + wr * 64 + m * 16 + fr;
;                 float o[4];
; #pragma unroll
;                 for (int e = 0; e < 4; ++e) {
;                     const float a1 = dppf<0x111>(ca[e]) + dppf<0x10F>(pa[e]), a2 = dppf<0x112>(ca[e]) + dppf<0x10E>(pa[e]);
;                     const float b1 = dppf<0x111>(cb[e]) + dppf<0x10F>(pb[e]), b2 = dppf<0x112>(cb[e]) + dppf<0x10E>(pb[e]);
;                     const float ya = fmaf(wa0[e], a2, fmaf(wa1[e], a1, fmaf(wa2[e], ca[e], ba[e])));
;                     const float yb = fmaf(wb0[e], b2, fmaf(wb1[e], b1, fmaf(wb2[e], cb[e], bb[e])));
;                     o[e] = silu_fast(ya) * yb; }
;                 if (m > 0 || fr >= 2) { u32x2 w; w.x = pk2(o[0], o[1]); w.y = pk2(o[2], o[3]); *(u32x2*)(E.d0 + (size_t)row * FFH + j0) = w; }
;                 if ((m == 0 && fr < 2) || (m == 3 && fr >= 14)) { float* hb = E.f0 + ((size_t)(row >> 6) * 4 + (m == 0 ? fr : fr - 12)) * FF2 + ncol; *(f32x4*)hb = ca; *(f32x4*)(hb + 4) = cb; }
;                 pa = ca; pb = cb;
	s_mov_b32 s80, 0x16000
	s_mov_b32 s81, 0
	v_lshl_add_u64 v[222:223], v[224:225], 0, s[80:81]
	v_mul_f32_e32 v208, v208, v216
	v_mul_f32_e32 v209, v209, v217
	v_mul_f32_e32 v210, v210, v218
	v_mul_f32_e32 v211, v211, v219
	v_mul_f32_e32 v208, v212, v208
	v_mul_f32_e32 v209, v213, v209
	v_mul_f32_e32 v210, v214, v210
	v_mul_f32_e32 v211, v215, v211
	v_cvt_pk_bf16_f32 v220, v208, v209
	v_cvt_pk_bf16_f32 v221, v210, v211
	global_store_dwordx2 v[222:223], v[220:221], off
	v_fma_f32 v160, v152, v100, v156
	v_fma_f32 v161, v153, v101, v157
	v_fma_f32 v162, v154, v102, v158
	v_fma_f32 v163, v155, v103, v159
	v_fma_f32 v164, v144, v88, v148
	v_fma_f32 v165, v145, v89, v149
	v_fma_f32 v166, v146, v90, v150
	v_fma_f32 v167, v147, v91, v151
	v_fmac_f32_dpp v160, v100, v140 row_shr:1 row_mask:0xf bank_mask:0xf
	v_fmac_f32_dpp v161, v101, v141 row_shr:1 row_mask:0xf bank_mask:0xf
	v_fmac_f32_dpp v162, v102, v142 row_shr:1 row_mask:0xf bank_mask:0xf
	v_fmac_f32_dpp v163, v103, v143 row_shr:1 row_mask:0xf bank_mask:0xf
	v_fmac_f32_dpp v164, v88, v132 row_shr:1 row_mask:0xf bank_mask:0xf
	v_fmac_f32_dpp v165, v89, v133 row_shr:1 row_mask:0xf bank_mask:0xf
	v_fmac_f32_dpp v166, v90, v134 row_shr:1 row_mask:0xf bank_mask:0xf
	v_fmac_f32_dpp v167, v91, v135 row_shr:1 row_mask:0xf bank_mask:0xf
	v_fmac_f32_dpp v160, v116, v140 row_shl:15 row_mask:0xf bank_mask:0xf
	v_fmac_f32_dpp v161, v117, v141 row_shl:15 row_mask:0xf bank_mask:0xf
	v_fmac_f32_dpp v162, v118, v142 row_shl:15 row_mask:0xf bank_mask:0xf
	v_fmac_f32_dpp v163, v119, v143 row_shl:15 row_mask:0xf bank_mask:0xf
	v_fmac_f32_dpp v164, v104, v132 row_shl:15 row_mask:0xf bank_mask:0xf
	v_fmac_f32_dpp v165, v105, v133 row_shl:15 row_mask:0xf bank_mask:0xf
	v_fmac_f32_dpp v166, v106, v134 row_shl:15 row_mask:0xf bank_mask:0xf
	v_fmac_f32_dpp v167, v107, v135 row_shl:15 row_mask:0xf bank_mask:0xf
	v_fmac_f32_dpp v160, v100, v136 row_shr:2 row_mask:0xf bank_mask:0xf
	v_fmac_f32_dpp v161, v101, v137 row_shr:2 row_mask:0xf bank_mask:0xf
	v_fmac_f32_dpp v162, v102, v138 row_shr:2 row_mask:0xf bank_mask:0xf
	v_fmac_f32_dpp v163, v103, v139 row_shr:2 row_mask:0xf bank_mask:0xf
	v_fmac_f32_dpp v164, v88, v128 row_shr:2 row_mask:0xf bank_mask:0xf
	v_fmac_f32_dpp v165, v89, v129 row_shr:2 row_mask:0xf bank_mask:0xf
	v_fmac_f32_dpp v166, v90, v130 row_shr:2 row_mask:0xf bank_mask:0xf
	v_fmac_f32_dpp v167, v91, v131 row_shr:2 row_mask:0xf bank_mask:0xf
	v_fmac_f32_dpp v160, v116, v136 row_shl:14 row_mask:0xf bank_mask:0xf
	v_fmac_f32_dpp v161, v117, v137 row_shl:14 row_mask:0xf bank_mask:0xf
	v_fmac_f32_dpp v162, v118, v138 row_shl:14 row_mask:0xf bank_mask:0xf
	v_fmac_f32_dpp v163, v119, v139 row_shl:14 row_mask:0xf bank_mask:0xf
	v_fmac_f32_dpp v164, v104, v128 row_shl:14 row_mask:0xf bank_mask:0xf
	v_fmac_f32_dpp v165, v105, v129 row_shl:14 row_mask:0xf bank_mask:0xf
	v_fmac_f32_dpp v166, v106, v130 row_shl:14 row_mask:0xf bank_mask:0xf
	v_fmac_f32_dpp v167, v107, v131 row_shl:14 row_mask:0xf bank_mask:0xf
	v_pk_mul_f32 v[168:169], v[160:161], s[98:99]
	v_pk_mul_f32 v[170:171], v[162:163], s[98:99]
	v_exp_f32_e32 v168, v168
	v_exp_f32_e32 v169, v169
	v_exp_f32_e32 v170, v170
	v_exp_f32_e32 v171, v171
	v_pk_add_f32 v[168:169], v[168:169], s[100:101]
	v_pk_add_f32 v[170:171], v[170:171], s[100:101]
	v_rcp_f32_e32 v168, v168
	v_rcp_f32_e32 v169, v169
	v_rcp_f32_e32 v170, v170
	v_rcp_f32_e32 v171, v171
	s_mov_b32 s80, 0x2c000
	s_mov_b32 s81, 0
	v_lshl_add_u64 v[174:175], v[224:225], 0, s[80:81]
	v_mul_f32_e32 v160, v160, v168
	v_mul_f32_e32 v161, v161, v169
	v_mul_f32_e32 v162, v162, v170
	v_mul_f32_e32 v163, v163, v171
	v_mul_f32_e32 v160, v164, v160
	v_mul_f32_e32 v161, v165, v161
	v_mul_f32_e32 v162, v166, v162
	v_mul_f32_e32 v163, v167, v163
	v_cvt_pk_bf16_f32 v172, v160, v161
	v_cvt_pk_bf16_f32 v173, v162, v163
	global_store_dwordx2 v[174:175], v[172:173], off
	v_fma_f32 v208, v152, v84, v156
	v_fma_f32 v209, v153, v85, v157
	v_fma_f32 v210, v154, v86, v158
	v_fma_f32 v211, v155, v87, v159
	v_fma_f32 v212, v144, v72, v148
	v_fma_f32 v213, v145, v73, v149
	v_fma_f32 v214, v146, v74, v150
	v_fma_f32 v215, v147, v75, v151
	v_fmac_f32_dpp v208, v84, v140 row_shr:1 row_mask:0xf bank_mask:0xf
	v_fmac_f32_dpp v209, v85, v141 row_shr:1 row_mask:0xf bank_mask:0xf
	v_fmac_f32_dpp v210, v86, v142 row_shr:1 row_mask:0xf bank_mask:0xf
	v_fmac_f32_dpp v211, v87, v143 row_shr:1 row_mask:0xf bank_mask:0xf
	v_fmac_f32_dpp v212, v72, v132 row_shr:1 row_mask:0xf bank_mask:0xf
	v_fmac_f32_dpp v213, v73, v133 row_shr:1 row_mask:0xf bank_mask:0xf
	v_fmac_f32_dpp v214, v74, v134 row_shr:1 row_mask:0xf bank_mask:0xf
	v_fmac_f32_dpp v215, v75, v135 row_shr:1 row_mask:0xf bank_mask:0xf
	v_fmac_f32_dpp v208, v100, v140 row_shl:15 row_mask:0xf bank_mask:0xf
	v_fmac_f32_dpp v209, v101, v141 row_shl:15 row_mask:0xf bank_mask:0xf
	v_fmac_f32_dpp v210, v102, v142 row_shl:15 row_mask:0xf bank_mask:0xf
	v_fmac_f32_dpp v211, v103, v143 row_shl:15 row_mask:0xf bank_mask:0xf
	v_fmac_f32_dpp v212, v88, v132 row_shl:15 row_mask:0xf bank_mask:0xf
	v_fmac_f32_dpp v213, v89, v133 row_shl:15 row_mask:0xf bank_mask:0xf
	v_fmac_f32_dpp v214, v90, v134 row_shl:15 row_mask:0xf bank_mask:0xf
	v_fmac_f32_dpp v215, v91, v135 row_shl:15 row_mask:0xf bank_mask:0xf
	v_fmac_f32_dpp v208, v84, v136 row_shr:2 row_mask:0xf bank_mask:0xf
	v_fmac_f32_dpp v209, v85, v137 row_shr:2 row_mask:0xf bank_mask:0xf
	v_fmac_f32_dpp v210, v86, v138 row_shr:2 row_mask:0xf bank_mask:0xf
	v_fmac_f32_dpp v211, v87, v139 row_shr:2 row_mask:0xf bank_mask:0xf
	v_fmac_f32_dpp v212, v72, v128 row_shr:2 row_mask:0xf bank_mask:0xf
	v_fmac_f32_dpp v213, v73, v129 row_shr:2 row_mask:0xf bank_mask:0xf
; DI float silu_fast(float x) { return x * __builtin_amdgcn_rcpf(1.f + __expf(-x)); }
; template <int CTRL> DI float dppf(float v) { return __builtin_bit_cast(float, __builtin_amdgcn_update_dpp(0, __builtin_bit_cast(int, v), CTRL, 0xf, 0xf, true)); }
; DI void Epi::fused(const f32x4 (&acc)[2][2][4][2], int pm, int pn, int wr, int wc, int fr, int fq) const {
;     ...
;         const int ncol = pn * 256 + bj * 128 + wc * 32 + 8 * fq, j0 = (ncol >> 3) * 4;
;         const f32x4 wa0 = *(const f32x4*)(E.cf0 + j0), wa1 = *(const f32x4*)(E.cf0 + FF2 + j0), wa2 = *(const f32x4*)(E.cf0 + 2 * FF2 + j0);
;         const f32x4 wb0 = *(const f32x4*)(E.cf0 + FFH + j0), wb1 = *(const f32x4*)(E.cf0 + FF2 + FFH + j0), wb2 = *(const f32x4*)(E.cf0 + 2 * FF2 + FFH + j0);
;         const f32x4 ba = *(const f32x4*)(E.cf1 + j0), bb = *(const f32x4*)(E.cf1 + FFH + j0);
; #pragma unroll
;         for (int ai = 0; ai < 2; ++ai) {
;             f32x4 pa = (f32x4){0.f, 0.f, 0.f, 0.f}, pb = pa;
; #pragma unroll
;             for (int m = 0; m < 4; ++m) {
;                 const f32x4 ca = acc[ai][bj][m][0], cb = acc[ai][bj][m][1];
;                 const int row = pm * 256 + ai * 128 + wr * 64 + m * 16 + fr;
;                 float o[4];
; #pragma unroll
;                 for (int e = 0; e < 4; ++e) {
;                     const float a1 = dppf<0x111>(ca[e]) + dppf<0x10F>(pa[e]), a2 = dppf<0x112>(ca[e]) + dppf<0x10E>(pa[e]);
;                     const float b1 = dppf<0x111>(cb[e]) + dppf<0x10F>(pb[e]), b2 = dppf<0x112>(cb[e]) + dppf<0x10E>(pb[e]);
;                     const float ya = fmaf(wa0[e], a2, fmaf(wa1[e], a1, fmaf(wa2[e], ca[e], ba[e])));
;                     const float yb = fmaf(wb0[e], b2, fmaf(wb1[e], b1, fmaf(wb2[e], cb[e], bb[e])));
;                     o[e] = silu_fast(ya) * yb; }
;                 if (m > 0 || fr >= 2) { u32x2 w; w.x = pk2(o[0], o[1]); w.y = pk2(o[2], o[3]); *(u32x2*)(E.d0 + (size_t)row * FFH + j0) = w; }
;                 if ((m == 0 && fr < 2) || (m == 3 && fr >= 14)) { float* hb = E.f0 + ((size_t)(row >> 6) * 4 + (m == 0 ? fr : fr - 12)) * FF2 + ncol; *(f32x4*)hb = ca; *(f32x4*)(hb + 4) = cb; }
;                 pa = ca; pb = cb;
	v_fmac_f32_dpp v214, v74, v130 row_shr:2 row_mask:0xf bank_mask:0xf
	v_fmac_f32_dpp v215, v75, v131 row_shr:2 row_mask:0xf bank_mask:0xf
	v_fmac_f32_dpp v208, v100, v136 row_shl:14 row_mask:0xf bank_mask:0xf
	v_fmac_f32_dpp v209, v101, v137 row_shl:14 row_mask:0xf bank_mask:0xf
	v_fmac_f32_dpp v210, v102, v138 row_shl:14 row_mask:0xf bank_mask:0xf
	v_fmac_f32_dpp v211, v103, v139 row_shl:14 row_mask:0xf bank_mask:0xf
	v_fmac_f32_dpp v212, v88, v128 row_shl:14 row_mask:0xf bank_mask:0xf
	v_fmac_f32_dpp v213, v89, v129 row_shl:14 row_mask:0xf bank_mask:0xf
	v_fmac_f32_dpp v214, v90, v130 row_shl:14 row_mask:0xf bank_mask:0xf
	v_fmac_f32_dpp v215, v91, v131 row_shl:14 row_mask:0xf bank_mask:0xf
	v_pk_mul_f32 v[216:217], v[208:209], s[98:99]
	v_pk_mul_f32 v[218:219], v[210:211], s[98:99]
	v_exp_f32_e32 v216, v216
	v_exp_f32_e32 v217, v217
	v_exp_f32_e32 v218, v218
	v_exp_f32_e32 v219, v219
	v_pk_add_f32 v[216:217], v[216:217], s[100:101]
	v_pk_add_f32 v[218:219], v[218:219], s[100:101]
	v_rcp_f32_e32 v216, v216
	v_rcp_f32_e32 v217, v217
	v_rcp_f32_e32 v218, v218
	v_rcp_f32_e32 v219, v219
	s_mov_b32 s80, 0x42000
	s_mov_b32 s81, 0
	v_lshl_add_u64 v[222:223], v[224:225], 0, s[80:81]
	v_mul_f32_e32 v208, v208, v216
	v_mul_f32_e32 v209, v209, v217
	v_mul_f32_e32 v210, v210, v218
	v_mul_f32_e32 v211, v211, v219
	v_mul_f32_e32 v208, v212, v208
	v_mul_f32_e32 v209, v213, v209
	v_mul_f32_e32 v210, v214, v210
	v_mul_f32_e32 v211, v215, v211
	v_cvt_pk_bf16_f32 v220, v208, v209
	v_cvt_pk_bf16_f32 v221, v210, v211
	global_store_dwordx2 v[222:223], v[220:221], off
	s_ashr_i32 s80, s71, 6
	s_lshl_b32 s80, s80, 2
	v_add_u32_e32 v226, s80, v190
	v_mov_b64_e32 v[222:223], s[8:9]
	s_movk_i32 s80, 0x5800
	v_mad_i64_i32 v[222:223], s[78:79], v226, s80, v[222:223]
	v_lshl_add_u64 v[222:223], v[228:229], 2, v[222:223]
	s_and_saveexec_b64 s[76:77], s[42:43]
	global_store_dwordx4 v[222:223], v[84:87], off
	global_store_dwordx4 v[222:223], v[72:75], off offset:16
	s_or_b64 exec, exec, s[76:77]
	v_add_u32_e32 v238, 0x80, v240
	v_lshlrev_b32_e32 v238, 1, v238
	v_mov_b32_e32 v239, 0
	v_lshl_add_u64 v[84:85], s[22:23], 0, v[238:239]
	global_load_dwordx4 v[84:87], v[84:85], off
	v_readlane_b32 s76, v254, 54
	v_readlane_b32 s77, v254, 55
	s_nop 1
	v_lshl_add_u64 v[88:89], s[76:77], 0, v[238:239]
	global_load_dwordx4 v[88:91], v[88:89], off
	v_readlane_b32 s76, v254, 56
	v_readlane_b32 s77, v254, 57
	s_nop 1
	v_lshl_add_u64 v[100:101], s[76:77], 0, v[238:239]
	global_load_dwordx4 v[100:103], v[100:101], off
	v_readlane_b32 s76, v255, 4
	v_readlane_b32 s77, v255, 5
	s_nop 1
	v_lshl_add_u64 v[104:105], s[76:77], 0, v[238:239]
	global_load_dwordx4 v[104:107], v[104:105], off
	v_readlane_b32 s76, v255, 6
	v_readlane_b32 s77, v255, 7
	s_nop 1
	v_lshl_add_u64 v[116:117], s[76:77], 0, v[238:239]
	global_load_dwordx4 v[116:119], v[116:117], off
	v_readlane_b32 s76, v255, 8
	v_readlane_b32 s77, v255, 9
	s_nop 1
	v_lshl_add_u64 v[120:121], s[76:77], 0, v[238:239]
	global_load_dwordx4 v[120:123], v[120:121], off
	v_readlane_b32 s76, v254, 49
	v_readlane_b32 s77, v254, 50
	s_nop 1
	v_lshl_add_u64 v[124:125], s[76:77], 0, v[238:239]
	global_load_dwordx4 v[124:127], v[124:125], off
	v_lshl_add_u64 v[72:73], s[72:73], 0, v[238:239]
	global_load_dwordx4 v[72:75], v[72:73], off
	v_add_u32_e32 v228, 128, v199
	v_mov_b64_e32 v[224:225], s[12:13]
	s_movk_i32 s80, 0x1600
	v_mad_i64_i32 v[224:225], s[78:79], v228, s80, v[224:225]
	v_mov_b32_e32 v228, v240
	v_mov_b32_e32 v229, 0
	v_lshl_add_u64 v[224:225], v[228:229], 0, v[224:225]
	v_fma_f32 v160, v152, v60, v156
	v_fma_f32 v161, v153, v61, v157
	v_fma_f32 v162, v154, v62, v158
	v_fma_f32 v163, v155, v63, v159
	v_fma_f32 v164, v144, v56, v148
	v_fma_f32 v165, v145, v57, v149
	v_fma_f32 v166, v146, v58, v150
	v_fma_f32 v167, v147, v59, v151
	v_fmac_f32_dpp v160, v60, v140 row_shr:1 row_mask:0xf bank_mask:0xf
	v_fmac_f32_dpp v161, v61, v141 row_shr:1 row_mask:0xf bank_mask:0xf
	v_fmac_f32_dpp v162, v62, v142 row_shr:1 row_mask:0xf bank_mask:0xf
	v_fmac_f32_dpp v163, v63, v143 row_shr:1 row_mask:0xf bank_mask:0xf
	v_fmac_f32_dpp v164, v56, v132 row_shr:1 row_mask:0xf bank_mask:0xf
	v_fmac_f32_dpp v165, v57, v133 row_shr:1 row_mask:0xf bank_mask:0xf
	v_fmac_f32_dpp v166, v58, v134 row_shr:1 row_mask:0xf bank_mask:0xf
	v_fmac_f32_dpp v167, v59, v135 row_shr:1 row_mask:0xf bank_mask:0xf
	v_fmac_f32_dpp v160, v60, v136 row_shr:2 row_mask:0xf bank_mask:0xf
	v_fmac_f32_dpp v161, v61, v137 row_shr:2 row_mask:0xf bank_mask:0xf
	v_fmac_f32_dpp v162, v62, v138 row_shr:2 row_mask:0xf bank_mask:0xf
	v_fmac_f32_dpp v163, v63, v139 row_shr:2 row_mask:0xf bank_mask:0xf
	v_fmac_f32_dpp v164, v56, v128 row_shr:2 row_mask:0xf bank_mask:0xf
	v_fmac_f32_dpp v165, v57, v129 row_shr:2 row_mask:0xf bank_mask:0xf
	v_fmac_f32_dpp v166, v58, v130 row_shr:2 row_mask:0xf bank_mask:0xf
	v_fmac_f32_dpp v167, v59, v131 row_shr:2 row_mask:0xf bank_mask:0xf
	v_pk_mul_f32 v[168:169], v[160:161], s[98:99]
	v_pk_mul_f32 v[170:171], v[162:163], s[98:99]
	v_exp_f32_e32 v168, v168
	v_exp_f32_e32 v169, v169
	v_exp_f32_e32 v170, v170
	v_exp_f32_e32 v171, v171
	v_pk_add_f32 v[168:169], v[168:169], s[100:101]
	v_pk_add_f32 v[170:171], v[170:171], s[100:101]
	v_rcp_f32_e32 v168, v168
	v_rcp_f32_e32 v169, v169
	v_rcp_f32_e32 v170, v170
	v_rcp_f32_e32 v171, v171
	v_mov_b64_e32 v[174:175], v[224:225]
	v_mul_f32_e32 v160, v160, v168
	v_mul_f32_e32 v161, v161, v169
	v_mul_f32_e32 v162, v162, v170
	v_mul_f32_e32 v163, v163, v171
	v_mul_f32_e32 v160, v164, v160
	v_mul_f32_e32 v161, v165, v161
	v_mul_f32_e32 v162, v166, v162
	v_mul_f32_e32 v163, v167, v163
	v_cvt_pk_bf16_f32 v172, v160, v161
; DI float silu_fast(float x) { return x * __builtin_amdgcn_rcpf(1.f + __expf(-x)); }
; template <int CTRL> DI float dppf(float v) { return __builtin_bit_cast(float, __builtin_amdgcn_update_dpp(0, __builtin_bit_cast(int, v), CTRL, 0xf, 0xf, true)); }
; DI void Epi::fused(const f32x4 (&acc)[2][2][4][2], int pm, int pn, int wr, int wc, int fr, int fq) const {
;     ...
;             for (int m = 0; m < 4; ++m) {
;                 const f32x4 ca = acc[ai][bj][m][0], cb = acc[ai][bj][m][1];
;                 const int row = pm * 256 + ai * 128 + wr * 64 + m * 16 + fr;
;                 float o[4];
; #pragma unroll
;                 for (int e = 0; e < 4; ++e) {
;                     const float a1 = dppf<0x111>(ca[e]) + dppf<0x10F>(pa[e]), a2 = dppf<0x112>(ca[e]) + dppf<0x10E>(pa[e]);
;                     const float b1 = dppf<0x111>(cb[e]) + dppf<0x10F>(pb[e]), b2 = dppf<0x112>(cb[e]) + dppf<0x10E>(pb[e]);
;                     const float ya = fmaf(wa0[e], a2, fmaf(wa1[e], a1, fmaf(wa2[e], ca[e], ba[e])));
;                     const float yb = fmaf(wb0[e], b2, fmaf(wb1[e], b1, fmaf(wb2[e], cb[e], bb[e])));
;                     o[e] = silu_fast(ya) * yb; }
;                 if (m > 0 || fr >= 2) { u32x2 w; w.x = pk2(o[0], o[1]); w.y = pk2(o[2], o[3]); *(u32x2*)(E.d0 + (size_t)row * FFH + j0) = w; }
;                 if ((m == 0 && fr < 2) || (m == 3 && fr >= 14)) { float* hb = E.f0 + ((size_t)(row >> 6) * 4 + (m == 0 ? fr : fr - 12)) * FF2 + ncol; *(f32x4*)hb = ca; *(f32x4*)(hb + 4) = cb; }
;                 pa = ca; pb = cb;
	v_cvt_pk_bf16_f32 v173, v162, v163
	s_and_saveexec_b64 s[76:77], s[38:39]
	global_store_dwordx2 v[174:175], v[172:173], off
	s_or_b64 exec, exec, s[76:77]
	s_ashr_i32 s80, s71, 6
	s_lshl_b32 s80, s80, 2
	s_add_i32 s80, s80, 8
	v_add_u32_e32 v226, s80, v188
	v_mov_b64_e32 v[174:175], s[8:9]
	s_movk_i32 s80, 0x5800
	v_mad_i64_i32 v[174:175], s[78:79], v226, s80, v[174:175]
	v_lshl_add_u64 v[174:175], v[228:229], 2, v[174:175]
	s_and_saveexec_b64 s[76:77], s[40:41]
	global_store_dwordx4 v[174:175], v[60:63], off
	global_store_dwordx4 v[174:175], v[56:59], off offset:16
	s_or_b64 exec, exec, s[76:77]
	v_fma_f32 v208, v152, v52, v156
	v_fma_f32 v209, v153, v53, v157
	v_fma_f32 v210, v154, v54, v158
	v_fma_f32 v211, v155, v55, v159
	v_fma_f32 v212, v144, v40, v148
	v_fma_f32 v213, v145, v41, v149
	v_fma_f32 v214, v146, v42, v150
	v_fma_f32 v215, v147, v43, v151
	v_fmac_f32_dpp v208, v52, v140 row_shr:1 row_mask:0xf bank_mask:0xf
	v_fmac_f32_dpp v209, v53, v141 row_shr:1 row_mask:0xf bank_mask:0xf
	v_fmac_f32_dpp v210, v54, v142 row_shr:1 row_mask:0xf bank_mask:0xf
	v_fmac_f32_dpp v211, v55, v143 row_shr:1 row_mask:0xf bank_mask:0xf
	v_fmac_f32_dpp v212, v40, v132 row_shr:1 row_mask:0xf bank_mask:0xf
	v_fmac_f32_dpp v213, v41, v133 row_shr:1 row_mask:0xf bank_mask:0xf
	v_fmac_f32_dpp v214, v42, v134 row_shr:1 row_mask:0xf bank_mask:0xf
	v_fmac_f32_dpp v215, v43, v135 row_shr:1 row_mask:0xf bank_mask:0xf
	v_fmac_f32_dpp v208, v60, v140 row_shl:15 row_mask:0xf bank_mask:0xf
	v_fmac_f32_dpp v209, v61, v141 row_shl:15 row_mask:0xf bank_mask:0xf
	v_fmac_f32_dpp v210, v62, v142 row_shl:15 row_mask:0xf bank_mask:0xf
	v_fmac_f32_dpp v211, v63, v143 row_shl:15 row_mask:0xf bank_mask:0xf
	v_fmac_f32_dpp v212, v56, v132 row_shl:15 row_mask:0xf bank_mask:0xf
	v_fmac_f32_dpp v213, v57, v133 row_shl:15 row_mask:0xf bank_mask:0xf
	v_fmac_f32_dpp v214, v58, v134 row_shl:15 row_mask:0xf bank_mask:0xf
	v_fmac_f32_dpp v215, v59, v135 row_shl:15 row_mask:0xf bank_mask:0xf
	v_fmac_f32_dpp v208, v52, v136 row_shr:2 row_mask:0xf bank_mask:0xf
	v_fmac_f32_dpp v209, v53, v137 row_shr:2 row_mask:0xf bank_mask:0xf
	v_fmac_f32_dpp v210, v54, v138 row_shr:2 row_mask:0xf bank_mask:0xf
	v_fmac_f32_dpp v211, v55, v139 row_shr:2 row_mask:0xf bank_mask:0xf
	v_fmac_f32_dpp v212, v40, v128 row_shr:2 row_mask:0xf bank_mask:0xf
	v_fmac_f32_dpp v213, v41, v129 row_shr:2 row_mask:0xf bank_mask:0xf
	v_fmac_f32_dpp v214, v42, v130 row_shr:2 row_mask:0xf bank_mask:0xf
	v_fmac_f32_dpp v215, v43, v131 row_shr:2 row_mask:0xf bank_mask:0xf
	v_fmac_f32_dpp v208, v60, v136 row_shl:14 row_mask:0xf bank_mask:0xf
	v_fmac_f32_dpp v209, v61, v137 row_shl:14 row_mask:0xf bank_mask:0xf
	v_fmac_f32_dpp v210, v62, v138 row_shl:14 row_mask:0xf bank_mask:0xf
	v_fmac_f32_dpp v211, v63, v139 row_shl:14 row_mask:0xf bank_mask:0xf
	v_fmac_f32_dpp v212, v56, v128 row_shl:14 row_mask:0xf bank_mask:0xf
	v_fmac_f32_dpp v213, v57, v129 row_shl:14 row_mask:0xf bank_mask:0xf
	v_fmac_f32_dpp v214, v58, v130 row_shl:14 row_mask:0xf bank_mask:0xf
	v_fmac_f32_dpp v215, v59, v131 row_shl:14 row_mask:0xf bank_mask:0xf
	v_pk_mul_f32 v[216:217], v[208:209], s[98:99]
	v_pk_mul_f32 v[218:219], v[210:211], s[98:99]
	v_exp_f32_e32 v216, v216
	v_exp_f32_e32 v217, v217
	v_exp_f32_e32 v218, v218
	v_exp_f32_e32 v219, v219
	v_pk_add_f32 v[216:217], v[216:217], s[100:101]
	v_pk_add_f32 v[218:219], v[218:219], s[100:101]
	v_rcp_f32_e32 v216, v216
	v_rcp_f32_e32 v217, v217
	v_rcp_f32_e32 v218, v218
	v_rcp_f32_e32 v219, v219
	s_mov_b32 s80, 0x16000
	s_mov_b32 s81, 0
	v_lshl_add_u64 v[222:223], v[224:225], 0, s[80:81]
	v_mul_f32_e32 v208, v208, v216
	v_mul_f32_e32 v209, v209, v217
	v_mul_f32_e32 v210, v210, v218
	v_mul_f32_e32 v211, v211, v219
	v_mul_f32_e32 v208, v212, v208
	v_mul_f32_e32 v209, v213, v209
	v_mul_f32_e32 v210, v214, v210
	v_mul_f32_e32 v211, v215, v211
	v_cvt_pk_bf16_f32 v220, v208, v209
	v_cvt_pk_bf16_f32 v221, v210, v211
	global_store_dwordx2 v[222:223], v[220:221], off
	v_fma_f32 v160, v152, v36, v156
	v_fma_f32 v161, v153, v37, v157
	v_fma_f32 v162, v154, v38, v158
	v_fma_f32 v163, v155, v39, v159
	v_fma_f32 v164, v144, v16, v148
	v_fma_f32 v165, v145, v17, v149
	v_fma_f32 v166, v146, v18, v150
	v_fma_f32 v167, v147, v19, v151
	v_fmac_f32_dpp v160, v36, v140 row_shr:1 row_mask:0xf bank_mask:0xf
	v_fmac_f32_dpp v161, v37, v141 row_shr:1 row_mask:0xf bank_mask:0xf
	v_fmac_f32_dpp v162, v38, v142 row_shr:1 row_mask:0xf bank_mask:0xf
	v_fmac_f32_dpp v163, v39, v143 row_shr:1 row_mask:0xf bank_mask:0xf
	v_fmac_f32_dpp v164, v16, v132 row_shr:1 row_mask:0xf bank_mask:0xf
	v_fmac_f32_dpp v165, v17, v133 row_shr:1 row_mask:0xf bank_mask:0xf
	v_fmac_f32_dpp v166, v18, v134 row_shr:1 row_mask:0xf bank_mask:0xf
	v_fmac_f32_dpp v167, v19, v135 row_shr:1 row_mask:0xf bank_mask:0xf
	v_fmac_f32_dpp v160, v52, v140 row_shl:15 row_mask:0xf bank_mask:0xf
	v_fmac_f32_dpp v161, v53, v141 row_shl:15 row_mask:0xf bank_mask:0xf
	v_fmac_f32_dpp v162, v54, v142 row_shl:15 row_mask:0xf bank_mask:0xf
	v_fmac_f32_dpp v163, v55, v143 row_shl:15 row_mask:0xf bank_mask:0xf
	v_fmac_f32_dpp v164, v40, v132 row_shl:15 row_mask:0xf bank_mask:0xf
	v_fmac_f32_dpp v165, v41, v133 row_shl:15 row_mask:0xf bank_mask:0xf
	v_fmac_f32_dpp v166, v42, v134 row_shl:15 row_mask:0xf bank_mask:0xf
	v_fmac_f32_dpp v167, v43, v135 row_shl:15 row_mask:0xf bank_mask:0xf
	v_fmac_f32_dpp v160, v36, v136 row_shr:2 row_mask:0xf bank_mask:0xf
	v_fmac_f32_dpp v161, v37, v137 row_shr:2 row_mask:0xf bank_mask:0xf
	v_fmac_f32_dpp v162, v38, v138 row_shr:2 row_mask:0xf bank_mask:0xf
	v_fmac_f32_dpp v163, v39, v139 row_shr:2 row_mask:0xf bank_mask:0xf
; DI float silu_fast(float x) { return x * __builtin_amdgcn_rcpf(1.f + __expf(-x)); }
; template <int CTRL> DI float dppf(float v) { return __builtin_bit_cast(float, __builtin_amdgcn_update_dpp(0, __builtin_bit_cast(int, v), CTRL, 0xf, 0xf, true)); }
; DI void Epi::fused(const f32x4 (&acc)[2][2][4][2], int pm, int pn, int wr, int wc, int fr, int fq) const {
;     ...
;             for (int m = 0; m < 4; ++m) {
;                 const f32x4 ca = acc[ai][bj][m][0], cb = acc[ai][bj][m][1];
;                 const int row = pm * 256 + ai * 128 + wr * 64 + m * 16 + fr;
;                 float o[4];
; #pragma unroll
;                 for (int e = 0; e < 4; ++e) {
;                     const float a1 = dppf<0x111>(ca[e]) + dppf<0x10F>(pa[e]), a2 = dppf<0x112>(ca[e]) + dppf<0x10E>(pa[e]);
;                     const float b1 = dppf<0x111>(cb[e]) + dppf<0x10F>(pb[e]), b2 = dppf<0x112>(cb[e]) + dppf<0x10E>(pb[e]);
;                     const float ya = fmaf(wa0[e], a2, fmaf(wa1[e], a1, fmaf(wa2[e], ca[e], ba[e])));
;                     const float yb = fmaf(wb0[e], b2, fmaf(wb1[e], b1, fmaf(wb2[e], cb[e], bb[e])));
;                     o[e] = silu_fast(ya) * yb; }
;                 if (m > 0 || fr >= 2) { u32x2 w; w.x = pk2(o[0], o[1]); w.y = pk2(o[2], o[3]); *(u32x2*)(E.d0 + (size_t)row * FFH + j0) = w; }
;                 if ((m == 0 && fr < 2) || (m == 3 && fr >= 14)) { float* hb = E.f0 + ((size_t)(row >> 6) * 4 + (m == 0 ? fr : fr - 12)) * FF2 + ncol; *(f32x4*)hb = ca; *(f32x4*)(hb + 4) = cb; }
;                 pa = ca; pb = cb;
	v_fmac_f32_dpp v164, v16, v128 row_shr:2 row_mask:0xf bank_mask:0xf
	v_fmac_f32_dpp v165, v17, v129 row_shr:2 row_mask:0xf bank_mask:0xf
	v_fmac_f32_dpp v166, v18, v130 row_shr:2 row_mask:0xf bank_mask:0xf
	v_fmac_f32_dpp v167, v19, v131 row_shr:2 row_mask:0xf bank_mask:0xf
	v_fmac_f32_dpp v160, v52, v136 row_shl:14 row_mask:0xf bank_mask:0xf
	v_fmac_f32_dpp v161, v53, v137 row_shl:14 row_mask:0xf bank_mask:0xf
	v_fmac_f32_dpp v162, v54, v138 row_shl:14 row_mask:0xf bank_mask:0xf
	v_fmac_f32_dpp v163, v55, v139 row_shl:14 row_mask:0xf bank_mask:0xf
	v_fmac_f32_dpp v164, v40, v128 row_shl:14 row_mask:0xf bank_mask:0xf
	v_fmac_f32_dpp v165, v41, v129 row_shl:14 row_mask:0xf bank_mask:0xf
	v_fmac_f32_dpp v166, v42, v130 row_shl:14 row_mask:0xf bank_mask:0xf
	v_fmac_f32_dpp v167, v43, v131 row_shl:14 row_mask:0xf bank_mask:0xf
	v_pk_mul_f32 v[168:169], v[160:161], s[98:99]
	v_pk_mul_f32 v[170:171], v[162:163], s[98:99]
	v_exp_f32_e32 v168, v168
	v_exp_f32_e32 v169, v169
	v_exp_f32_e32 v170, v170
	v_exp_f32_e32 v171, v171
	v_pk_add_f32 v[168:169], v[168:169], s[100:101]
	v_pk_add_f32 v[170:171], v[170:171], s[100:101]
	v_rcp_f32_e32 v168, v168
	v_rcp_f32_e32 v169, v169
	v_rcp_f32_e32 v170, v170
	v_rcp_f32_e32 v171, v171
	s_mov_b32 s80, 0x2c000
	s_mov_b32 s81, 0
	v_lshl_add_u64 v[174:175], v[224:225], 0, s[80:81]
	v_mul_f32_e32 v160, v160, v168
	v_mul_f32_e32 v161, v161, v169
	v_mul_f32_e32 v162, v162, v170
	v_mul_f32_e32 v163, v163, v171
	v_mul_f32_e32 v160, v164, v160
	v_mul_f32_e32 v161, v165, v161
	v_mul_f32_e32 v162, v166, v162
	v_mul_f32_e32 v163, v167, v163
	v_cvt_pk_bf16_f32 v172, v160, v161
	v_cvt_pk_bf16_f32 v173, v162, v163
	global_store_dwordx2 v[174:175], v[172:173], off
	v_fma_f32 v208, v152, v12, v156
	v_fma_f32 v209, v153, v13, v157
	v_fma_f32 v210, v154, v14, v158
	v_fma_f32 v211, v155, v15, v159
	v_fma_f32 v212, v144, v0, v148
	v_fma_f32 v213, v145, v1, v149
	v_fma_f32 v214, v146, v2, v150
	v_fma_f32 v215, v147, v3, v151
	v_fmac_f32_dpp v208, v12, v140 row_shr:1 row_mask:0xf bank_mask:0xf
	v_fmac_f32_dpp v209, v13, v141 row_shr:1 row_mask:0xf bank_mask:0xf
	v_fmac_f32_dpp v210, v14, v142 row_shr:1 row_mask:0xf bank_mask:0xf
	v_fmac_f32_dpp v211, v15, v143 row_shr:1 row_mask:0xf bank_mask:0xf
	v_fmac_f32_dpp v212, v0, v132 row_shr:1 row_mask:0xf bank_mask:0xf
	v_fmac_f32_dpp v213, v1, v133 row_shr:1 row_mask:0xf bank_mask:0xf
	v_fmac_f32_dpp v214, v2, v134 row_shr:1 row_mask:0xf bank_mask:0xf
	v_fmac_f32_dpp v215, v3, v135 row_shr:1 row_mask:0xf bank_mask:0xf
	v_fmac_f32_dpp v208, v36, v140 row_shl:15 row_mask:0xf bank_mask:0xf
	v_fmac_f32_dpp v209, v37, v141 row_shl:15 row_mask:0xf bank_mask:0xf
	v_fmac_f32_dpp v210, v38, v142 row_shl:15 row_mask:0xf bank_mask:0xf
	v_fmac_f32_dpp v211, v39, v143 row_shl:15 row_mask:0xf bank_mask:0xf
	v_fmac_f32_dpp v212, v16, v132 row_shl:15 row_mask:0xf bank_mask:0xf
	v_fmac_f32_dpp v213, v17, v133 row_shl:15 row_mask:0xf bank_mask:0xf
	v_fmac_f32_dpp v214, v18, v134 row_shl:15 row_mask:0xf bank_mask:0xf
	v_fmac_f32_dpp v215, v19, v135 row_shl:15 row_mask:0xf bank_mask:0xf
	v_fmac_f32_dpp v208, v12, v136 row_shr:2 row_mask:0xf bank_mask:0xf
	v_fmac_f32_dpp v209, v13, v137 row_shr:2 row_mask:0xf bank_mask:0xf
	v_fmac_f32_dpp v210, v14, v138 row_shr:2 row_mask:0xf bank_mask:0xf
	v_fmac_f32_dpp v211, v15, v139 row_shr:2 row_mask:0xf bank_mask:0xf
	v_fmac_f32_dpp v212, v0, v128 row_shr:2 row_mask:0xf bank_mask:0xf
	v_fmac_f32_dpp v213, v1, v129 row_shr:2 row_mask:0xf bank_mask:0xf
	v_fmac_f32_dpp v214, v2, v130 row_shr:2 row_mask:0xf bank_mask:0xf
	v_fmac_f32_dpp v215, v3, v131 row_shr:2 row_mask:0xf bank_mask:0xf
	v_fmac_f32_dpp v208, v36, v136 row_shl:14 row_mask:0xf bank_mask:0xf
	v_fmac_f32_dpp v209, v37, v137 row_shl:14 row_mask:0xf bank_mask:0xf
	v_fmac_f32_dpp v210, v38, v138 row_shl:14 row_mask:0xf bank_mask:0xf
	v_fmac_f32_dpp v211, v39, v139 row_shl:14 row_mask:0xf bank_mask:0xf
	v_fmac_f32_dpp v212, v16, v128 row_shl:14 row_mask:0xf bank_mask:0xf
	v_fmac_f32_dpp v213, v17, v129 row_shl:14 row_mask:0xf bank_mask:0xf
	v_fmac_f32_dpp v214, v18, v130 row_shl:14 row_mask:0xf bank_mask:0xf
	v_fmac_f32_dpp v215, v19, v131 row_shl:14 row_mask:0xf bank_mask:0xf
	v_pk_mul_f32 v[216:217], v[208:209], s[98:99]
	v_pk_mul_f32 v[218:219], v[210:211], s[98:99]
	v_exp_f32_e32 v216, v216
	v_exp_f32_e32 v217, v217
	v_exp_f32_e32 v218, v218
	v_exp_f32_e32 v219, v219
	v_pk_add_f32 v[216:217], v[216:217], s[100:101]
	v_pk_add_f32 v[218:219], v[218:219], s[100:101]
	v_rcp_f32_e32 v216, v216
	v_rcp_f32_e32 v217, v217
	v_rcp_f32_e32 v218, v218
	v_rcp_f32_e32 v219, v219
	s_mov_b32 s80, 0x42000
	s_mov_b32 s81, 0
	v_lshl_add_u64 v[222:223], v[224:225], 0, s[80:81]
	v_mul_f32_e32 v208, v208, v216
	v_mul_f32_e32 v209, v209, v217
	v_mul_f32_e32 v210, v210, v218
	v_mul_f32_e32 v211, v211, v219
	v_mul_f32_e32 v208, v212, v208
	v_mul_f32_e32 v209, v213, v209
	v_mul_f32_e32 v210, v214, v210
	v_mul_f32_e32 v211, v215, v211
	v_cvt_pk_bf16_f32 v220, v208, v209
	v_cvt_pk_bf16_f32 v221, v210, v211
	global_store_dwordx2 v[222:223], v[220:221], off
	s_ashr_i32 s80, s71, 6
	s_lshl_b32 s80, s80, 2
	s_add_i32 s80, s80, 8
	v_add_u32_e32 v226, s80, v190
	v_mov_b64_e32 v[222:223], s[8:9]
	s_movk_i32 s80, 0x5800
	v_mad_i64_i32 v[222:223], s[78:79], v226, s80, v[222:223]
	v_lshl_add_u64 v[222:223], v[228:229], 2, v[222:223]
	s_and_saveexec_b64 s[76:77], s[42:43]
	global_store_dwordx4 v[222:223], v[12:15], off
	global_store_dwordx4 v[222:223], v[0:3], off offset:16
	s_or_b64 exec, exec, s[76:77]
	v_mov_b32_e32 v228, v199
	v_mov_b64_e32 v[224:225], s[12:13]
	s_movk_i32 s80, 0x1600
	v_mad_i64_i32 v[224:225], s[78:79], v228, s80, v[224:225]
	v_add_u32_e32 v228, 128, v240
	v_mov_b32_e32 v229, 0
	v_lshl_add_u64 v[224:225], v[228:229], 0, v[224:225]
	s_waitcnt vmcnt(8)
; DI float silu_fast(float x) { return x * __builtin_amdgcn_rcpf(1.f + __expf(-x)); }
; template <int CTRL> DI float dppf(float v) { return __builtin_bit_cast(float, __builtin_amdgcn_update_dpp(0, __builtin_bit_cast(int, v), CTRL, 0xf, 0xf, true)); }
; DI void Epi::fused(const f32x4 (&acc)[2][2][4][2], int pm, int pn, int wr, int wc, int fr, int fq) const {
;     ...
;             for (int m = 0; m < 4; ++m) {
;                 const f32x4 ca = acc[ai][bj][m][0], cb = acc[ai][bj][m][1];
;                 const int row = pm * 256 + ai * 128 + wr * 64 + m * 16 + fr;
;                 float o[4];
; #pragma unroll
;                 for (int e = 0; e < 4; ++e) {
;                     const float a1 = dppf<0x111>(ca[e]) + dppf<0x10F>(pa[e]), a2 = dppf<0x112>(ca[e]) + dppf<0x10E>(pa[e]);
;                     const float b1 = dppf<0x111>(cb[e]) + dppf<0x10F>(pb[e]), b2 = dppf<0x112>(cb[e]) + dppf<0x10E>(pb[e]);
;                     const float ya = fmaf(wa0[e], a2, fmaf(wa1[e], a1, fmaf(wa2[e], ca[e], ba[e])));
;                     const float yb = fmaf(wb0[e], b2, fmaf(wb1[e], b1, fmaf(wb2[e], cb[e], bb[e])));
;                     o[e] = silu_fast(ya) * yb; }
;                 if (m > 0 || fr >= 2) { u32x2 w; w.x = pk2(o[0], o[1]); w.y = pk2(o[2], o[3]); *(u32x2*)(E.d0 + (size_t)row * FFH + j0) = w; }
;                 if ((m == 0 && fr < 2) || (m == 3 && fr >= 14)) { float* hb = E.f0 + ((size_t)(row >> 6) * 4 + (m == 0 ? fr : fr - 12)) * FF2 + ncol; *(f32x4*)hb = ca; *(f32x4*)(hb + 4) = cb; }
;                 pa = ca; pb = cb;
	v_fma_f32 v160, v100, v112, v124
	v_fma_f32 v161, v101, v113, v125
	v_fma_f32 v162, v102, v114, v126
	v_fma_f32 v163, v103, v115, v127
	v_fma_f32 v164, v120, v108, v72
	v_fma_f32 v165, v121, v109, v73
	v_fma_f32 v166, v122, v110, v74
	v_fma_f32 v167, v123, v111, v75
	v_fmac_f32_dpp v160, v112, v88 row_shr:1 row_mask:0xf bank_mask:0xf
	v_fmac_f32_dpp v161, v113, v89 row_shr:1 row_mask:0xf bank_mask:0xf
	v_fmac_f32_dpp v162, v114, v90 row_shr:1 row_mask:0xf bank_mask:0xf
	v_fmac_f32_dpp v163, v115, v91 row_shr:1 row_mask:0xf bank_mask:0xf
	v_fmac_f32_dpp v164, v108, v116 row_shr:1 row_mask:0xf bank_mask:0xf
	v_fmac_f32_dpp v165, v109, v117 row_shr:1 row_mask:0xf bank_mask:0xf
	v_fmac_f32_dpp v166, v110, v118 row_shr:1 row_mask:0xf bank_mask:0xf
	v_fmac_f32_dpp v167, v111, v119 row_shr:1 row_mask:0xf bank_mask:0xf
	v_fmac_f32_dpp v160, v112, v84 row_shr:2 row_mask:0xf bank_mask:0xf
	v_fmac_f32_dpp v161, v113, v85 row_shr:2 row_mask:0xf bank_mask:0xf
	v_fmac_f32_dpp v162, v114, v86 row_shr:2 row_mask:0xf bank_mask:0xf
	v_fmac_f32_dpp v163, v115, v87 row_shr:2 row_mask:0xf bank_mask:0xf
	v_fmac_f32_dpp v164, v108, v104 row_shr:2 row_mask:0xf bank_mask:0xf
	v_fmac_f32_dpp v165, v109, v105 row_shr:2 row_mask:0xf bank_mask:0xf
	v_fmac_f32_dpp v166, v110, v106 row_shr:2 row_mask:0xf bank_mask:0xf
	v_fmac_f32_dpp v167, v111, v107 row_shr:2 row_mask:0xf bank_mask:0xf
	v_pk_mul_f32 v[168:169], v[160:161], s[98:99]
	v_pk_mul_f32 v[170:171], v[162:163], s[98:99]
	v_exp_f32_e32 v168, v168
	v_exp_f32_e32 v169, v169
	v_exp_f32_e32 v170, v170
	v_exp_f32_e32 v171, v171
	v_pk_add_f32 v[168:169], v[168:169], s[100:101]
	v_pk_add_f32 v[170:171], v[170:171], s[100:101]
	v_rcp_f32_e32 v168, v168
	v_rcp_f32_e32 v169, v169
	v_rcp_f32_e32 v170, v170
	v_rcp_f32_e32 v171, v171
	v_mov_b64_e32 v[174:175], v[224:225]
	v_mul_f32_e32 v160, v160, v168
	v_mul_f32_e32 v161, v161, v169
	v_mul_f32_e32 v162, v162, v170
	v_mul_f32_e32 v163, v163, v171
	v_mul_f32_e32 v160, v164, v160
	v_mul_f32_e32 v161, v165, v161
	v_mul_f32_e32 v162, v166, v162
	v_mul_f32_e32 v163, v167, v163
	v_cvt_pk_bf16_f32 v172, v160, v161
	v_cvt_pk_bf16_f32 v173, v162, v163
	s_and_saveexec_b64 s[76:77], s[38:39]
	global_store_dwordx2 v[174:175], v[172:173], off
	s_or_b64 exec, exec, s[76:77]
	s_ashr_i32 s80, s71, 6
	s_lshl_b32 s80, s80, 2
	v_add_u32_e32 v226, s80, v188
	v_mov_b64_e32 v[174:175], s[8:9]
	s_movk_i32 s80, 0x5800
	v_mad_i64_i32 v[174:175], s[78:79], v226, s80, v[174:175]
	v_lshl_add_u64 v[174:175], v[228:229], 2, v[174:175]
	s_and_saveexec_b64 s[76:77], s[40:41]
	global_store_dwordx4 v[174:175], v[112:115], off
	global_store_dwordx4 v[174:175], v[108:111], off offset:16
	s_or_b64 exec, exec, s[76:77]
	v_fma_f32 v208, v100, v96, v124
	v_fma_f32 v209, v101, v97, v125
	v_fma_f32 v210, v102, v98, v126
	v_fma_f32 v211, v103, v99, v127
	v_fma_f32 v212, v120, v92, v72
	v_fma_f32 v213, v121, v93, v73
	v_fma_f32 v214, v122, v94, v74
	v_fma_f32 v215, v123, v95, v75
	v_fmac_f32_dpp v208, v96, v88 row_shr:1 row_mask:0xf bank_mask:0xf
	v_fmac_f32_dpp v209, v97, v89 row_shr:1 row_mask:0xf bank_mask:0xf
	v_fmac_f32_dpp v210, v98, v90 row_shr:1 row_mask:0xf bank_mask:0xf
	v_fmac_f32_dpp v211, v99, v91 row_shr:1 row_mask:0xf bank_mask:0xf
	v_fmac_f32_dpp v212, v92, v116 row_shr:1 row_mask:0xf bank_mask:0xf
	v_fmac_f32_dpp v213, v93, v117 row_shr:1 row_mask:0xf bank_mask:0xf
	v_fmac_f32_dpp v214, v94, v118 row_shr:1 row_mask:0xf bank_mask:0xf
	v_fmac_f32_dpp v215, v95, v119 row_shr:1 row_mask:0xf bank_mask:0xf
	v_fmac_f32_dpp v208, v112, v88 row_shl:15 row_mask:0xf bank_mask:0xf
	v_fmac_f32_dpp v209, v113, v89 row_shl:15 row_mask:0xf bank_mask:0xf
	v_fmac_f32_dpp v210, v114, v90 row_shl:15 row_mask:0xf bank_mask:0xf
	v_fmac_f32_dpp v211, v115, v91 row_shl:15 row_mask:0xf bank_mask:0xf
	v_fmac_f32_dpp v212, v108, v116 row_shl:15 row_mask:0xf bank_mask:0xf
	v_fmac_f32_dpp v213, v109, v117 row_shl:15 row_mask:0xf bank_mask:0xf
	v_fmac_f32_dpp v214, v110, v118 row_shl:15 row_mask:0xf bank_mask:0xf
	v_fmac_f32_dpp v215, v111, v119 row_shl:15 row_mask:0xf bank_mask:0xf
	v_fmac_f32_dpp v208, v96, v84 row_shr:2 row_mask:0xf bank_mask:0xf
	v_fmac_f32_dpp v209, v97, v85 row_shr:2 row_mask:0xf bank_mask:0xf
	v_fmac_f32_dpp v210, v98, v86 row_shr:2 row_mask:0xf bank_mask:0xf
	v_fmac_f32_dpp v211, v99, v87 row_shr:2 row_mask:0xf bank_mask:0xf
	v_fmac_f32_dpp v212, v92, v104 row_shr:2 row_mask:0xf bank_mask:0xf
	v_fmac_f32_dpp v213, v93, v105 row_shr:2 row_mask:0xf bank_mask:0xf
	v_fmac_f32_dpp v214, v94, v106 row_shr:2 row_mask:0xf bank_mask:0xf
	v_fmac_f32_dpp v215, v95, v107 row_shr:2 row_mask:0xf bank_mask:0xf
	v_fmac_f32_dpp v208, v112, v84 row_shl:14 row_mask:0xf bank_mask:0xf
	v_fmac_f32_dpp v209, v113, v85 row_shl:14 row_mask:0xf bank_mask:0xf
	v_fmac_f32_dpp v210, v114, v86 row_shl:14 row_mask:0xf bank_mask:0xf
	v_fmac_f32_dpp v211, v115, v87 row_shl:14 row_mask:0xf bank_mask:0xf
	v_fmac_f32_dpp v212, v108, v104 row_shl:14 row_mask:0xf bank_mask:0xf
	v_fmac_f32_dpp v213, v109, v105 row_shl:14 row_mask:0xf bank_mask:0xf
	v_fmac_f32_dpp v214, v110, v106 row_shl:14 row_mask:0xf bank_mask:0xf
	v_fmac_f32_dpp v215, v111, v107 row_shl:14 row_mask:0xf bank_mask:0xf
	v_pk_mul_f32 v[216:217], v[208:209], s[98:99]
	v_pk_mul_f32 v[218:219], v[210:211], s[98:99]
	v_exp_f32_e32 v216, v216
	v_exp_f32_e32 v217, v217
	v_exp_f32_e32 v218, v218
	v_exp_f32_e32 v219, v219
	v_pk_add_f32 v[216:217], v[216:217], s[100:101]
	v_pk_add_f32 v[218:219], v[218:219], s[100:101]
	v_rcp_f32_e32 v216, v216
	v_rcp_f32_e32 v217, v217
	v_rcp_f32_e32 v218, v218
	v_rcp_f32_e32 v219, v219
	s_mov_b32 s80, 0x16000
	s_mov_b32 s81, 0
; DI float silu_fast(float x) { return x * __builtin_amdgcn_rcpf(1.f + __expf(-x)); }
; template <int CTRL> DI float dppf(float v) { return __builtin_bit_cast(float, __builtin_amdgcn_update_dpp(0, __builtin_bit_cast(int, v), CTRL, 0xf, 0xf, true)); }
; DI void Epi::fused(const f32x4 (&acc)[2][2][4][2], int pm, int pn, int wr, int wc, int fr, int fq) const {
;     ...
;             for (int m = 0; m < 4; ++m) {
;                 const f32x4 ca = acc[ai][bj][m][0], cb = acc[ai][bj][m][1];
;                 const int row = pm * 256 + ai * 128 + wr * 64 + m * 16 + fr;
;                 float o[4];
; #pragma unroll
;                 for (int e = 0; e < 4; ++e) {
;                     const float a1 = dppf<0x111>(ca[e]) + dppf<0x10F>(pa[e]), a2 = dppf<0x112>(ca[e]) + dppf<0x10E>(pa[e]);
;                     const float b1 = dppf<0x111>(cb[e]) + dppf<0x10F>(pb[e]), b2 = dppf<0x112>(cb[e]) + dppf<0x10E>(pb[e]);
;                     const float ya = fmaf(wa0[e], a2, fmaf(wa1[e], a1, fmaf(wa2[e], ca[e], ba[e])));
;                     const float yb = fmaf(wb0[e], b2, fmaf(wb1[e], b1, fmaf(wb2[e], cb[e], bb[e])));
;                     o[e] = silu_fast(ya) * yb; }
;                 if (m > 0 || fr >= 2) { u32x2 w; w.x = pk2(o[0], o[1]); w.y = pk2(o[2], o[3]); *(u32x2*)(E.d0 + (size_t)row * FFH + j0) = w; }
;                 if ((m == 0 && fr < 2) || (m == 3 && fr >= 14)) { float* hb = E.f0 + ((size_t)(row >> 6) * 4 + (m == 0 ? fr : fr - 12)) * FF2 + ncol; *(f32x4*)hb = ca; *(f32x4*)(hb + 4) = cb; }
;                 pa = ca; pb = cb;
	v_lshl_add_u64 v[222:223], v[224:225], 0, s[80:81]
	v_mul_f32_e32 v208, v208, v216
	v_mul_f32_e32 v209, v209, v217
	v_mul_f32_e32 v210, v210, v218
	v_mul_f32_e32 v211, v211, v219
	v_mul_f32_e32 v208, v212, v208
	v_mul_f32_e32 v209, v213, v209
	v_mul_f32_e32 v210, v214, v210
	v_mul_f32_e32 v211, v215, v211
	v_cvt_pk_bf16_f32 v220, v208, v209
	v_cvt_pk_bf16_f32 v221, v210, v211
	global_store_dwordx2 v[222:223], v[220:221], off
	v_fma_f32 v160, v100, v80, v124
	v_fma_f32 v161, v101, v81, v125
	v_fma_f32 v162, v102, v82, v126
	v_fma_f32 v163, v103, v83, v127
	v_fma_f32 v164, v120, v76, v72
	v_fma_f32 v165, v121, v77, v73
	v_fma_f32 v166, v122, v78, v74
	v_fma_f32 v167, v123, v79, v75
	v_fmac_f32_dpp v160, v80, v88 row_shr:1 row_mask:0xf bank_mask:0xf
	v_fmac_f32_dpp v161, v81, v89 row_shr:1 row_mask:0xf bank_mask:0xf
	v_fmac_f32_dpp v162, v82, v90 row_shr:1 row_mask:0xf bank_mask:0xf
	v_fmac_f32_dpp v163, v83, v91 row_shr:1 row_mask:0xf bank_mask:0xf
	v_fmac_f32_dpp v164, v76, v116 row_shr:1 row_mask:0xf bank_mask:0xf
	v_fmac_f32_dpp v165, v77, v117 row_shr:1 row_mask:0xf bank_mask:0xf
	v_fmac_f32_dpp v166, v78, v118 row_shr:1 row_mask:0xf bank_mask:0xf
	v_fmac_f32_dpp v167, v79, v119 row_shr:1 row_mask:0xf bank_mask:0xf
	v_fmac_f32_dpp v160, v96, v88 row_shl:15 row_mask:0xf bank_mask:0xf
	v_fmac_f32_dpp v161, v97, v89 row_shl:15 row_mask:0xf bank_mask:0xf
	v_fmac_f32_dpp v162, v98, v90 row_shl:15 row_mask:0xf bank_mask:0xf
	v_fmac_f32_dpp v163, v99, v91 row_shl:15 row_mask:0xf bank_mask:0xf
	v_fmac_f32_dpp v164, v92, v116 row_shl:15 row_mask:0xf bank_mask:0xf
	v_fmac_f32_dpp v165, v93, v117 row_shl:15 row_mask:0xf bank_mask:0xf
	v_fmac_f32_dpp v166, v94, v118 row_shl:15 row_mask:0xf bank_mask:0xf
	v_fmac_f32_dpp v167, v95, v119 row_shl:15 row_mask:0xf bank_mask:0xf
	v_fmac_f32_dpp v160, v80, v84 row_shr:2 row_mask:0xf bank_mask:0xf
	v_fmac_f32_dpp v161, v81, v85 row_shr:2 row_mask:0xf bank_mask:0xf
	v_fmac_f32_dpp v162, v82, v86 row_shr:2 row_mask:0xf bank_mask:0xf
	v_fmac_f32_dpp v163, v83, v87 row_shr:2 row_mask:0xf bank_mask:0xf
	v_fmac_f32_dpp v164, v76, v104 row_shr:2 row_mask:0xf bank_mask:0xf
	v_fmac_f32_dpp v165, v77, v105 row_shr:2 row_mask:0xf bank_mask:0xf
	v_fmac_f32_dpp v166, v78, v106 row_shr:2 row_mask:0xf bank_mask:0xf
	v_fmac_f32_dpp v167, v79, v107 row_shr:2 row_mask:0xf bank_mask:0xf
	v_fmac_f32_dpp v160, v96, v84 row_shl:14 row_mask:0xf bank_mask:0xf
	v_fmac_f32_dpp v161, v97, v85 row_shl:14 row_mask:0xf bank_mask:0xf
	v_fmac_f32_dpp v162, v98, v86 row_shl:14 row_mask:0xf bank_mask:0xf
	v_fmac_f32_dpp v163, v99, v87 row_shl:14 row_mask:0xf bank_mask:0xf
	v_fmac_f32_dpp v164, v92, v104 row_shl:14 row_mask:0xf bank_mask:0xf
	v_fmac_f32_dpp v165, v93, v105 row_shl:14 row_mask:0xf bank_mask:0xf
	v_fmac_f32_dpp v166, v94, v106 row_shl:14 row_mask:0xf bank_mask:0xf
	v_fmac_f32_dpp v167, v95, v107 row_shl:14 row_mask:0xf bank_mask:0xf
	v_pk_mul_f32 v[168:169], v[160:161], s[98:99]
	v_pk_mul_f32 v[170:171], v[162:163], s[98:99]
	v_exp_f32_e32 v168, v168
	v_exp_f32_e32 v169, v169
	v_exp_f32_e32 v170, v170
	v_exp_f32_e32 v171, v171
	v_pk_add_f32 v[168:169], v[168:169], s[100:101]
	v_pk_add_f32 v[170:171], v[170:171], s[100:101]
	v_rcp_f32_e32 v168, v168
	v_rcp_f32_e32 v169, v169
	v_rcp_f32_e32 v170, v170
	v_rcp_f32_e32 v171, v171
	s_mov_b32 s80, 0x2c000
	s_mov_b32 s81, 0
	v_lshl_add_u64 v[174:175], v[224:225], 0, s[80:81]
	v_mul_f32_e32 v160, v160, v168
	v_mul_f32_e32 v161, v161, v169
	v_mul_f32_e32 v162, v162, v170
	v_mul_f32_e32 v163, v163, v171
	v_mul_f32_e32 v160, v164, v160
	v_mul_f32_e32 v161, v165, v161
	v_mul_f32_e32 v162, v166, v162
	v_mul_f32_e32 v163, v167, v163
	v_cvt_pk_bf16_f32 v172, v160, v161
	v_cvt_pk_bf16_f32 v173, v162, v163
	global_store_dwordx2 v[174:175], v[172:173], off
	v_fma_f32 v208, v100, v68, v124
	v_fma_f32 v209, v101, v69, v125
	v_fma_f32 v210, v102, v70, v126
	v_fma_f32 v211, v103, v71, v127
	v_fma_f32 v212, v120, v64, v72
	v_fma_f32 v213, v121, v65, v73
	v_fma_f32 v214, v122, v66, v74
	v_fma_f32 v215, v123, v67, v75
	v_fmac_f32_dpp v208, v68, v88 row_shr:1 row_mask:0xf bank_mask:0xf
	v_fmac_f32_dpp v209, v69, v89 row_shr:1 row_mask:0xf bank_mask:0xf
	v_fmac_f32_dpp v210, v70, v90 row_shr:1 row_mask:0xf bank_mask:0xf
	v_fmac_f32_dpp v211, v71, v91 row_shr:1 row_mask:0xf bank_mask:0xf
	v_fmac_f32_dpp v212, v64, v116 row_shr:1 row_mask:0xf bank_mask:0xf
	v_fmac_f32_dpp v213, v65, v117 row_shr:1 row_mask:0xf bank_mask:0xf
	v_fmac_f32_dpp v214, v66, v118 row_shr:1 row_mask:0xf bank_mask:0xf
	v_fmac_f32_dpp v215, v67, v119 row_shr:1 row_mask:0xf bank_mask:0xf
	v_fmac_f32_dpp v208, v80, v88 row_shl:15 row_mask:0xf bank_mask:0xf
	v_fmac_f32_dpp v209, v81, v89 row_shl:15 row_mask:0xf bank_mask:0xf
	v_fmac_f32_dpp v210, v82, v90 row_shl:15 row_mask:0xf bank_mask:0xf
	v_fmac_f32_dpp v211, v83, v91 row_shl:15 row_mask:0xf bank_mask:0xf
	v_fmac_f32_dpp v212, v76, v116 row_shl:15 row_mask:0xf bank_mask:0xf
	v_fmac_f32_dpp v213, v77, v117 row_shl:15 row_mask:0xf bank_mask:0xf
	v_fmac_f32_dpp v214, v78, v118 row_shl:15 row_mask:0xf bank_mask:0xf
	v_fmac_f32_dpp v215, v79, v119 row_shl:15 row_mask:0xf bank_mask:0xf
	v_fmac_f32_dpp v208, v68, v84 row_shr:2 row_mask:0xf bank_mask:0xf
	v_fmac_f32_dpp v209, v69, v85 row_shr:2 row_mask:0xf bank_mask:0xf
	v_fmac_f32_dpp v210, v70, v86 row_shr:2 row_mask:0xf bank_mask:0xf
	v_fmac_f32_dpp v211, v71, v87 row_shr:2 row_mask:0xf bank_mask:0xf
	v_fmac_f32_dpp v212, v64, v104 row_shr:2 row_mask:0xf bank_mask:0xf
	v_fmac_f32_dpp v213, v65, v105 row_shr:2 row_mask:0xf bank_mask:0xf
	v_fmac_f32_dpp v214, v66, v106 row_shr:2 row_mask:0xf bank_mask:0xf
; DI float silu_fast(float x) { return x * __builtin_amdgcn_rcpf(1.f + __expf(-x)); }
; template <int CTRL> DI float dppf(float v) { return __builtin_bit_cast(float, __builtin_amdgcn_update_dpp(0, __builtin_bit_cast(int, v), CTRL, 0xf, 0xf, true)); }
; DI void Epi::fused(const f32x4 (&acc)[2][2][4][2], int pm, int pn, int wr, int wc, int fr, int fq) const {
;     ...
;             for (int m = 0; m < 4; ++m) {
;                 const f32x4 ca = acc[ai][bj][m][0], cb = acc[ai][bj][m][1];
;                 const int row = pm * 256 + ai * 128 + wr * 64 + m * 16 + fr;
;                 float o[4];
; #pragma unroll
;                 for (int e = 0; e < 4; ++e) {
;                     const float a1 = dppf<0x111>(ca[e]) + dppf<0x10F>(pa[e]), a2 = dppf<0x112>(ca[e]) + dppf<0x10E>(pa[e]);
;                     const float b1 = dppf<0x111>(cb[e]) + dppf<0x10F>(pb[e]), b2 = dppf<0x112>(cb[e]) + dppf<0x10E>(pb[e]);
;                     const float ya = fmaf(wa0[e], a2, fmaf(wa1[e], a1, fmaf(wa2[e], ca[e], ba[e])));
;                     const float yb = fmaf(wb0[e], b2, fmaf(wb1[e], b1, fmaf(wb2[e], cb[e], bb[e])));
;                     o[e] = silu_fast(ya) * yb; }
;                 if (m > 0 || fr >= 2) { u32x2 w; w.x = pk2(o[0], o[1]); w.y = pk2(o[2], o[3]); *(u32x2*)(E.d0 + (size_t)row * FFH + j0) = w; }
;                 if ((m == 0 && fr < 2) || (m == 3 && fr >= 14)) { float* hb = E.f0 + ((size_t)(row >> 6) * 4 + (m == 0 ? fr : fr - 12)) * FF2 + ncol; *(f32x4*)hb = ca; *(f32x4*)(hb + 4) = cb; }
;                 pa = ca; pb = cb;
	v_fmac_f32_dpp v215, v67, v107 row_shr:2 row_mask:0xf bank_mask:0xf
	v_fmac_f32_dpp v208, v80, v84 row_shl:14 row_mask:0xf bank_mask:0xf
	v_fmac_f32_dpp v209, v81, v85 row_shl:14 row_mask:0xf bank_mask:0xf
	v_fmac_f32_dpp v210, v82, v86 row_shl:14 row_mask:0xf bank_mask:0xf
	v_fmac_f32_dpp v211, v83, v87 row_shl:14 row_mask:0xf bank_mask:0xf
	v_fmac_f32_dpp v212, v76, v104 row_shl:14 row_mask:0xf bank_mask:0xf
	v_fmac_f32_dpp v213, v77, v105 row_shl:14 row_mask:0xf bank_mask:0xf
	v_fmac_f32_dpp v214, v78, v106 row_shl:14 row_mask:0xf bank_mask:0xf
	v_fmac_f32_dpp v215, v79, v107 row_shl:14 row_mask:0xf bank_mask:0xf
	v_pk_mul_f32 v[216:217], v[208:209], s[98:99]
	v_pk_mul_f32 v[218:219], v[210:211], s[98:99]
	v_exp_f32_e32 v216, v216
	v_exp_f32_e32 v217, v217
	v_exp_f32_e32 v218, v218
	v_exp_f32_e32 v219, v219
	v_pk_add_f32 v[216:217], v[216:217], s[100:101]
	v_pk_add_f32 v[218:219], v[218:219], s[100:101]
	v_rcp_f32_e32 v216, v216
	v_rcp_f32_e32 v217, v217
	v_rcp_f32_e32 v218, v218
	v_rcp_f32_e32 v219, v219
	s_mov_b32 s80, 0x42000
	s_mov_b32 s81, 0
	v_lshl_add_u64 v[222:223], v[224:225], 0, s[80:81]
	v_mul_f32_e32 v208, v208, v216
	v_mul_f32_e32 v209, v209, v217
	v_mul_f32_e32 v210, v210, v218
	v_mul_f32_e32 v211, v211, v219
	v_mul_f32_e32 v208, v212, v208
	v_mul_f32_e32 v209, v213, v209
	v_mul_f32_e32 v210, v214, v210
	v_mul_f32_e32 v211, v215, v211
	v_cvt_pk_bf16_f32 v220, v208, v209
	v_cvt_pk_bf16_f32 v221, v210, v211
	global_store_dwordx2 v[222:223], v[220:221], off
	s_ashr_i32 s80, s71, 6
	s_lshl_b32 s80, s80, 2
	v_add_u32_e32 v226, s80, v190
	v_mov_b64_e32 v[222:223], s[8:9]
	s_movk_i32 s80, 0x5800
	v_mad_i64_i32 v[222:223], s[78:79], v226, s80, v[222:223]
	v_lshl_add_u64 v[222:223], v[228:229], 2, v[222:223]
	s_and_saveexec_b64 s[76:77], s[42:43]
	global_store_dwordx4 v[222:223], v[68:71], off
	global_store_dwordx4 v[222:223], v[64:67], off offset:16
	s_or_b64 exec, exec, s[76:77]
	v_add_u32_e32 v228, 128, v199
	v_mov_b64_e32 v[224:225], s[12:13]
	s_movk_i32 s80, 0x1600
	v_mad_i64_i32 v[224:225], s[78:79], v228, s80, v[224:225]
	v_add_u32_e32 v228, 128, v240
	v_mov_b32_e32 v229, 0
	v_lshl_add_u64 v[224:225], v[228:229], 0, v[224:225]
	v_fma_f32 v160, v100, v48, v124
	v_fma_f32 v161, v101, v49, v125
	v_fma_f32 v162, v102, v50, v126
	v_fma_f32 v163, v103, v51, v127
	v_fma_f32 v164, v120, v44, v72
	v_fma_f32 v165, v121, v45, v73
	v_fma_f32 v166, v122, v46, v74
	v_fma_f32 v167, v123, v47, v75
	v_fmac_f32_dpp v160, v48, v88 row_shr:1 row_mask:0xf bank_mask:0xf
	v_fmac_f32_dpp v161, v49, v89 row_shr:1 row_mask:0xf bank_mask:0xf
	v_fmac_f32_dpp v162, v50, v90 row_shr:1 row_mask:0xf bank_mask:0xf
	v_fmac_f32_dpp v163, v51, v91 row_shr:1 row_mask:0xf bank_mask:0xf
	v_fmac_f32_dpp v164, v44, v116 row_shr:1 row_mask:0xf bank_mask:0xf
	v_fmac_f32_dpp v165, v45, v117 row_shr:1 row_mask:0xf bank_mask:0xf
	v_fmac_f32_dpp v166, v46, v118 row_shr:1 row_mask:0xf bank_mask:0xf
	v_fmac_f32_dpp v167, v47, v119 row_shr:1 row_mask:0xf bank_mask:0xf
	v_fmac_f32_dpp v160, v48, v84 row_shr:2 row_mask:0xf bank_mask:0xf
	v_fmac_f32_dpp v161, v49, v85 row_shr:2 row_mask:0xf bank_mask:0xf
	v_fmac_f32_dpp v162, v50, v86 row_shr:2 row_mask:0xf bank_mask:0xf
	v_fmac_f32_dpp v163, v51, v87 row_shr:2 row_mask:0xf bank_mask:0xf
	v_fmac_f32_dpp v164, v44, v104 row_shr:2 row_mask:0xf bank_mask:0xf
	v_fmac_f32_dpp v165, v45, v105 row_shr:2 row_mask:0xf bank_mask:0xf
	v_fmac_f32_dpp v166, v46, v106 row_shr:2 row_mask:0xf bank_mask:0xf
	v_fmac_f32_dpp v167, v47, v107 row_shr:2 row_mask:0xf bank_mask:0xf
	v_pk_mul_f32 v[168:169], v[160:161], s[98:99]
	v_pk_mul_f32 v[170:171], v[162:163], s[98:99]
	v_exp_f32_e32 v168, v168
	v_exp_f32_e32 v169, v169
	v_exp_f32_e32 v170, v170
	v_exp_f32_e32 v171, v171
	v_pk_add_f32 v[168:169], v[168:169], s[100:101]
	v_pk_add_f32 v[170:171], v[170:171], s[100:101]
	v_rcp_f32_e32 v168, v168
	v_rcp_f32_e32 v169, v169
	v_rcp_f32_e32 v170, v170
	v_rcp_f32_e32 v171, v171
	v_mov_b64_e32 v[174:175], v[224:225]
	v_mul_f32_e32 v160, v160, v168
	v_mul_f32_e32 v161, v161, v169
	v_mul_f32_e32 v162, v162, v170
	v_mul_f32_e32 v163, v163, v171
	v_mul_f32_e32 v160, v164, v160
	v_mul_f32_e32 v161, v165, v161
	v_mul_f32_e32 v162, v166, v162
	v_mul_f32_e32 v163, v167, v163
	v_cvt_pk_bf16_f32 v172, v160, v161
	v_cvt_pk_bf16_f32 v173, v162, v163
	s_and_saveexec_b64 s[76:77], s[38:39]
	global_store_dwordx2 v[174:175], v[172:173], off
	s_or_b64 exec, exec, s[76:77]
	s_ashr_i32 s80, s71, 6
	s_lshl_b32 s80, s80, 2
	s_add_i32 s80, s80, 8
	v_add_u32_e32 v226, s80, v188
	v_mov_b64_e32 v[174:175], s[8:9]
	s_movk_i32 s80, 0x5800
	v_mad_i64_i32 v[174:175], s[78:79], v226, s80, v[174:175]
	v_lshl_add_u64 v[174:175], v[228:229], 2, v[174:175]
	s_and_saveexec_b64 s[76:77], s[40:41]
	global_store_dwordx4 v[174:175], v[48:51], off
	global_store_dwordx4 v[174:175], v[44:47], off offset:16
	s_or_b64 exec, exec, s[76:77]
	v_fma_f32 v208, v100, v24, v124
	v_fma_f32 v209, v101, v25, v125
	v_fma_f32 v210, v102, v26, v126
	v_fma_f32 v211, v103, v27, v127
	v_fma_f32 v212, v120, v20, v72
	v_fma_f32 v213, v121, v21, v73
	v_fma_f32 v214, v122, v22, v74
	v_fma_f32 v215, v123, v23, v75
	v_fmac_f32_dpp v208, v24, v88 row_shr:1 row_mask:0xf bank_mask:0xf
	v_fmac_f32_dpp v209, v25, v89 row_shr:1 row_mask:0xf bank_mask:0xf
	v_fmac_f32_dpp v210, v26, v90 row_shr:1 row_mask:0xf bank_mask:0xf
	v_fmac_f32_dpp v211, v27, v91 row_shr:1 row_mask:0xf bank_mask:0xf
	v_fmac_f32_dpp v212, v20, v116 row_shr:1 row_mask:0xf bank_mask:0xf
	v_fmac_f32_dpp v213, v21, v117 row_shr:1 row_mask:0xf bank_mask:0xf
	v_fmac_f32_dpp v214, v22, v118 row_shr:1 row_mask:0xf bank_mask:0xf
; DI float silu_fast(float x) { return x * __builtin_amdgcn_rcpf(1.f + __expf(-x)); }
; template <int CTRL> DI float dppf(float v) { return __builtin_bit_cast(float, __builtin_amdgcn_update_dpp(0, __builtin_bit_cast(int, v), CTRL, 0xf, 0xf, true)); }
; DI void Epi::fused(const f32x4 (&acc)[2][2][4][2], int pm, int pn, int wr, int wc, int fr, int fq) const {
;     ...
;             for (int m = 0; m < 4; ++m) {
;                 const f32x4 ca = acc[ai][bj][m][0], cb = acc[ai][bj][m][1];
;                 const int row = pm * 256 + ai * 128 + wr * 64 + m * 16 + fr;
;                 float o[4];
; #pragma unroll
;                 for (int e = 0; e < 4; ++e) {
;                     const float a1 = dppf<0x111>(ca[e]) + dppf<0x10F>(pa[e]), a2 = dppf<0x112>(ca[e]) + dppf<0x10E>(pa[e]);
;                     const float b1 = dppf<0x111>(cb[e]) + dppf<0x10F>(pb[e]), b2 = dppf<0x112>(cb[e]) + dppf<0x10E>(pb[e]);
;                     const float ya = fmaf(wa0[e], a2, fmaf(wa1[e], a1, fmaf(wa2[e], ca[e], ba[e])));
;                     const float yb = fmaf(wb0[e], b2, fmaf(wb1[e], b1, fmaf(wb2[e], cb[e], bb[e])));
;                     o[e] = silu_fast(ya) * yb; }
;                 if (m > 0 || fr >= 2) { u32x2 w; w.x = pk2(o[0], o[1]); w.y = pk2(o[2], o[3]); *(u32x2*)(E.d0 + (size_t)row * FFH + j0) = w; }
;                 if ((m == 0 && fr < 2) || (m == 3 && fr >= 14)) { float* hb = E.f0 + ((size_t)(row >> 6) * 4 + (m == 0 ? fr : fr - 12)) * FF2 + ncol; *(f32x4*)hb = ca; *(f32x4*)(hb + 4) = cb; }
;                 pa = ca; pb = cb;
	v_fmac_f32_dpp v215, v23, v119 row_shr:1 row_mask:0xf bank_mask:0xf
	v_fmac_f32_dpp v208, v48, v88 row_shl:15 row_mask:0xf bank_mask:0xf
	v_fmac_f32_dpp v209, v49, v89 row_shl:15 row_mask:0xf bank_mask:0xf
	v_fmac_f32_dpp v210, v50, v90 row_shl:15 row_mask:0xf bank_mask:0xf
	v_fmac_f32_dpp v211, v51, v91 row_shl:15 row_mask:0xf bank_mask:0xf
	v_fmac_f32_dpp v212, v44, v116 row_shl:15 row_mask:0xf bank_mask:0xf
	v_fmac_f32_dpp v213, v45, v117 row_shl:15 row_mask:0xf bank_mask:0xf
	v_fmac_f32_dpp v214, v46, v118 row_shl:15 row_mask:0xf bank_mask:0xf
	v_fmac_f32_dpp v215, v47, v119 row_shl:15 row_mask:0xf bank_mask:0xf
	v_fmac_f32_dpp v208, v24, v84 row_shr:2 row_mask:0xf bank_mask:0xf
	v_fmac_f32_dpp v209, v25, v85 row_shr:2 row_mask:0xf bank_mask:0xf
	v_fmac_f32_dpp v210, v26, v86 row_shr:2 row_mask:0xf bank_mask:0xf
	v_fmac_f32_dpp v211, v27, v87 row_shr:2 row_mask:0xf bank_mask:0xf
	v_fmac_f32_dpp v212, v20, v104 row_shr:2 row_mask:0xf bank_mask:0xf
	v_fmac_f32_dpp v213, v21, v105 row_shr:2 row_mask:0xf bank_mask:0xf
	v_fmac_f32_dpp v214, v22, v106 row_shr:2 row_mask:0xf bank_mask:0xf
	v_fmac_f32_dpp v215, v23, v107 row_shr:2 row_mask:0xf bank_mask:0xf
	v_fmac_f32_dpp v208, v48, v84 row_shl:14 row_mask:0xf bank_mask:0xf
	v_fmac_f32_dpp v209, v49, v85 row_shl:14 row_mask:0xf bank_mask:0xf
	v_fmac_f32_dpp v210, v50, v86 row_shl:14 row_mask:0xf bank_mask:0xf
	v_fmac_f32_dpp v211, v51, v87 row_shl:14 row_mask:0xf bank_mask:0xf
	v_fmac_f32_dpp v212, v44, v104 row_shl:14 row_mask:0xf bank_mask:0xf
	v_fmac_f32_dpp v213, v45, v105 row_shl:14 row_mask:0xf bank_mask:0xf
	v_fmac_f32_dpp v214, v46, v106 row_shl:14 row_mask:0xf bank_mask:0xf
	v_fmac_f32_dpp v215, v47, v107 row_shl:14 row_mask:0xf bank_mask:0xf
	v_pk_mul_f32 v[216:217], v[208:209], s[98:99]
	v_pk_mul_f32 v[218:219], v[210:211], s[98:99]
	v_exp_f32_e32 v216, v216
	v_exp_f32_e32 v217, v217
	v_exp_f32_e32 v218, v218
	v_exp_f32_e32 v219, v219
	v_pk_add_f32 v[216:217], v[216:217], s[100:101]
	v_pk_add_f32 v[218:219], v[218:219], s[100:101]
	v_rcp_f32_e32 v216, v216
	v_rcp_f32_e32 v217, v217
	v_rcp_f32_e32 v218, v218
	v_rcp_f32_e32 v219, v219
	s_mov_b32 s80, 0x16000
	s_mov_b32 s81, 0
	v_lshl_add_u64 v[222:223], v[224:225], 0, s[80:81]
	v_mul_f32_e32 v208, v208, v216
	v_mul_f32_e32 v209, v209, v217
	v_mul_f32_e32 v210, v210, v218
	v_mul_f32_e32 v211, v211, v219
	v_mul_f32_e32 v208, v212, v208
	v_mul_f32_e32 v209, v213, v209
	v_mul_f32_e32 v210, v214, v210
	v_mul_f32_e32 v211, v215, v211
	v_cvt_pk_bf16_f32 v220, v208, v209
	v_cvt_pk_bf16_f32 v221, v210, v211
	global_store_dwordx2 v[222:223], v[220:221], off
	v_fma_f32 v160, v100, v28, v124
	v_fma_f32 v161, v101, v29, v125
	v_fma_f32 v162, v102, v30, v126
	v_fma_f32 v163, v103, v31, v127
	v_fma_f32 v164, v120, v32, v72
	v_fma_f32 v165, v121, v33, v73
	v_fma_f32 v166, v122, v34, v74
	v_fma_f32 v167, v123, v35, v75
	v_fmac_f32_dpp v160, v28, v88 row_shr:1 row_mask:0xf bank_mask:0xf
	v_fmac_f32_dpp v161, v29, v89 row_shr:1 row_mask:0xf bank_mask:0xf
	v_fmac_f32_dpp v162, v30, v90 row_shr:1 row_mask:0xf bank_mask:0xf
	v_fmac_f32_dpp v163, v31, v91 row_shr:1 row_mask:0xf bank_mask:0xf
	v_fmac_f32_dpp v164, v32, v116 row_shr:1 row_mask:0xf bank_mask:0xf
	v_fmac_f32_dpp v165, v33, v117 row_shr:1 row_mask:0xf bank_mask:0xf
	v_fmac_f32_dpp v166, v34, v118 row_shr:1 row_mask:0xf bank_mask:0xf
	v_fmac_f32_dpp v167, v35, v119 row_shr:1 row_mask:0xf bank_mask:0xf
	v_fmac_f32_dpp v160, v24, v88 row_shl:15 row_mask:0xf bank_mask:0xf
	v_fmac_f32_dpp v161, v25, v89 row_shl:15 row_mask:0xf bank_mask:0xf
	v_fmac_f32_dpp v162, v26, v90 row_shl:15 row_mask:0xf bank_mask:0xf
	v_fmac_f32_dpp v163, v27, v91 row_shl:15 row_mask:0xf bank_mask:0xf
	v_fmac_f32_dpp v164, v20, v116 row_shl:15 row_mask:0xf bank_mask:0xf
	v_fmac_f32_dpp v165, v21, v117 row_shl:15 row_mask:0xf bank_mask:0xf
	v_fmac_f32_dpp v166, v22, v118 row_shl:15 row_mask:0xf bank_mask:0xf
	v_fmac_f32_dpp v167, v23, v119 row_shl:15 row_mask:0xf bank_mask:0xf
	v_fmac_f32_dpp v160, v28, v84 row_shr:2 row_mask:0xf bank_mask:0xf
	v_fmac_f32_dpp v161, v29, v85 row_shr:2 row_mask:0xf bank_mask:0xf
	v_fmac_f32_dpp v162, v30, v86 row_shr:2 row_mask:0xf bank_mask:0xf
	v_fmac_f32_dpp v163, v31, v87 row_shr:2 row_mask:0xf bank_mask:0xf
	v_fmac_f32_dpp v164, v32, v104 row_shr:2 row_mask:0xf bank_mask:0xf
	v_fmac_f32_dpp v165, v33, v105 row_shr:2 row_mask:0xf bank_mask:0xf
	v_fmac_f32_dpp v166, v34, v106 row_shr:2 row_mask:0xf bank_mask:0xf
	v_fmac_f32_dpp v167, v35, v107 row_shr:2 row_mask:0xf bank_mask:0xf
	v_fmac_f32_dpp v160, v24, v84 row_shl:14 row_mask:0xf bank_mask:0xf
	v_fmac_f32_dpp v161, v25, v85 row_shl:14 row_mask:0xf bank_mask:0xf
	v_fmac_f32_dpp v162, v26, v86 row_shl:14 row_mask:0xf bank_mask:0xf
	v_fmac_f32_dpp v163, v27, v87 row_shl:14 row_mask:0xf bank_mask:0xf
	v_fmac_f32_dpp v164, v20, v104 row_shl:14 row_mask:0xf bank_mask:0xf
; DI float silu_fast(float x) { return x * __builtin_amdgcn_rcpf(1.f + __expf(-x)); }
; template <int CTRL> DI float dppf(float v) { return __builtin_bit_cast(float, __builtin_amdgcn_update_dpp(0, __builtin_bit_cast(int, v), CTRL, 0xf, 0xf, true)); }
; DI void Epi::fused(const f32x4 (&acc)[2][2][4][2], int pm, int pn, int wr, int wc, int fr, int fq) const {
;     ...
;             for (int m = 0; m < 4; ++m) {
;                 const f32x4 ca = acc[ai][bj][m][0], cb = acc[ai][bj][m][1];
;                 const int row = pm * 256 + ai * 128 + wr * 64 + m * 16 + fr;
;                 float o[4];
; #pragma unroll
;                 for (int e = 0; e < 4; ++e) {
;                     const float a1 = dppf<0x111>(ca[e]) + dppf<0x10F>(pa[e]), a2 = dppf<0x112>(ca[e]) + dppf<0x10E>(pa[e]);
;                     const float b1 = dppf<0x111>(cb[e]) + dppf<0x10F>(pb[e]), b2 = dppf<0x112>(cb[e]) + dppf<0x10E>(pb[e]);
;                     const float ya = fmaf(wa0[e], a2, fmaf(wa1[e], a1, fmaf(wa2[e], ca[e], ba[e])));
;                     const float yb = fmaf(wb0[e], b2, fmaf(wb1[e], b1, fmaf(wb2[e], cb[e], bb[e])));
;                     o[e] = silu_fast(ya) * yb; }
;                 if (m > 0 || fr >= 2) { u32x2 w; w.x = pk2(o[0], o[1]); w.y = pk2(o[2], o[3]); *(u32x2*)(E.d0 + (size_t)row * FFH + j0) = w; }
;                 if ((m == 0 && fr < 2) || (m == 3 && fr >= 14)) { float* hb = E.f0 + ((size_t)(row >> 6) * 4 + (m == 0 ? fr : fr - 12)) * FF2 + ncol; *(f32x4*)hb = ca; *(f32x4*)(hb + 4) = cb; }
;                 pa = ca; pb = cb;
	v_fmac_f32_dpp v165, v21, v105 row_shl:14 row_mask:0xf bank_mask:0xf
	v_fmac_f32_dpp v166, v22, v106 row_shl:14 row_mask:0xf bank_mask:0xf
	v_fmac_f32_dpp v167, v23, v107 row_shl:14 row_mask:0xf bank_mask:0xf
	v_pk_mul_f32 v[168:169], v[160:161], s[98:99]
	v_pk_mul_f32 v[170:171], v[162:163], s[98:99]
	v_exp_f32_e32 v168, v168
	v_exp_f32_e32 v169, v169
	v_exp_f32_e32 v170, v170
	v_exp_f32_e32 v171, v171
	v_pk_add_f32 v[168:169], v[168:169], s[100:101]
	v_pk_add_f32 v[170:171], v[170:171], s[100:101]
	v_rcp_f32_e32 v168, v168
	v_rcp_f32_e32 v169, v169
	v_rcp_f32_e32 v170, v170
	v_rcp_f32_e32 v171, v171
	s_mov_b32 s80, 0x2c000
	s_mov_b32 s81, 0
	v_lshl_add_u64 v[174:175], v[224:225], 0, s[80:81]
	v_mul_f32_e32 v160, v160, v168
	v_mul_f32_e32 v161, v161, v169
	v_mul_f32_e32 v162, v162, v170
	v_mul_f32_e32 v163, v163, v171
	v_mul_f32_e32 v160, v164, v160
	v_mul_f32_e32 v161, v165, v161
	v_mul_f32_e32 v162, v166, v162
	v_mul_f32_e32 v163, v167, v163
	v_cvt_pk_bf16_f32 v172, v160, v161
	v_cvt_pk_bf16_f32 v173, v162, v163
	global_store_dwordx2 v[174:175], v[172:173], off
	v_fma_f32 v208, v100, v8, v124
	v_fma_f32 v209, v101, v9, v125
	v_fma_f32 v210, v102, v10, v126
	v_fma_f32 v211, v103, v11, v127
	v_fma_f32 v212, v120, v4, v72
	v_fma_f32 v213, v121, v5, v73
	v_fma_f32 v214, v122, v6, v74
	v_fma_f32 v215, v123, v7, v75
	v_fmac_f32_dpp v208, v8, v88 row_shr:1 row_mask:0xf bank_mask:0xf
	v_fmac_f32_dpp v209, v9, v89 row_shr:1 row_mask:0xf bank_mask:0xf
	v_fmac_f32_dpp v210, v10, v90 row_shr:1 row_mask:0xf bank_mask:0xf
	v_fmac_f32_dpp v211, v11, v91 row_shr:1 row_mask:0xf bank_mask:0xf
	v_fmac_f32_dpp v212, v4, v116 row_shr:1 row_mask:0xf bank_mask:0xf
	v_fmac_f32_dpp v213, v5, v117 row_shr:1 row_mask:0xf bank_mask:0xf
	v_fmac_f32_dpp v214, v6, v118 row_shr:1 row_mask:0xf bank_mask:0xf
	v_fmac_f32_dpp v215, v7, v119 row_shr:1 row_mask:0xf bank_mask:0xf
	v_fmac_f32_dpp v208, v28, v88 row_shl:15 row_mask:0xf bank_mask:0xf
	v_fmac_f32_dpp v209, v29, v89 row_shl:15 row_mask:0xf bank_mask:0xf
	v_fmac_f32_dpp v210, v30, v90 row_shl:15 row_mask:0xf bank_mask:0xf
	v_fmac_f32_dpp v211, v31, v91 row_shl:15 row_mask:0xf bank_mask:0xf
	v_fmac_f32_dpp v212, v32, v116 row_shl:15 row_mask:0xf bank_mask:0xf
	v_fmac_f32_dpp v213, v33, v117 row_shl:15 row_mask:0xf bank_mask:0xf
	v_fmac_f32_dpp v214, v34, v118 row_shl:15 row_mask:0xf bank_mask:0xf
	v_fmac_f32_dpp v215, v35, v119 row_shl:15 row_mask:0xf bank_mask:0xf
	v_fmac_f32_dpp v208, v8, v84 row_shr:2 row_mask:0xf bank_mask:0xf
	v_fmac_f32_dpp v209, v9, v85 row_shr:2 row_mask:0xf bank_mask:0xf
	v_fmac_f32_dpp v210, v10, v86 row_shr:2 row_mask:0xf bank_mask:0xf
	v_fmac_f32_dpp v211, v11, v87 row_shr:2 row_mask:0xf bank_mask:0xf
	v_fmac_f32_dpp v212, v4, v104 row_shr:2 row_mask:0xf bank_mask:0xf
	v_fmac_f32_dpp v213, v5, v105 row_shr:2 row_mask:0xf bank_mask:0xf
	v_fmac_f32_dpp v214, v6, v106 row_shr:2 row_mask:0xf bank_mask:0xf
	v_fmac_f32_dpp v215, v7, v107 row_shr:2 row_mask:0xf bank_mask:0xf
	v_fmac_f32_dpp v208, v28, v84 row_shl:14 row_mask:0xf bank_mask:0xf
	v_fmac_f32_dpp v209, v29, v85 row_shl:14 row_mask:0xf bank_mask:0xf
	v_fmac_f32_dpp v210, v30, v86 row_shl:14 row_mask:0xf bank_mask:0xf
	v_fmac_f32_dpp v211, v31, v87 row_shl:14 row_mask:0xf bank_mask:0xf
	v_fmac_f32_dpp v212, v32, v104 row_shl:14 row_mask:0xf bank_mask:0xf
	v_fmac_f32_dpp v213, v33, v105 row_shl:14 row_mask:0xf bank_mask:0xf
	v_fmac_f32_dpp v214, v34, v106 row_shl:14 row_mask:0xf bank_mask:0xf
	v_fmac_f32_dpp v215, v35, v107 row_shl:14 row_mask:0xf bank_mask:0xf
	v_pk_mul_f32 v[216:217], v[208:209], s[98:99]
	v_pk_mul_f32 v[218:219], v[210:211], s[98:99]
	v_exp_f32_e32 v216, v216
	v_exp_f32_e32 v217, v217
	v_exp_f32_e32 v218, v218
	v_exp_f32_e32 v219, v219
	v_pk_add_f32 v[216:217], v[216:217], s[100:101]
	v_pk_add_f32 v[218:219], v[218:219], s[100:101]
	v_rcp_f32_e32 v216, v216
	v_rcp_f32_e32 v217, v217
	v_rcp_f32_e32 v218, v218
	v_rcp_f32_e32 v219, v219
	s_mov_b32 s80, 0x42000
	s_mov_b32 s81, 0
	v_lshl_add_u64 v[222:223], v[224:225], 0, s[80:81]
	v_mul_f32_e32 v208, v208, v216
	v_mul_f32_e32 v209, v209, v217
	v_mul_f32_e32 v210, v210, v218
	v_mul_f32_e32 v211, v211, v219
	v_mul_f32_e32 v208, v212, v208
	v_mul_f32_e32 v209, v213, v209
	v_mul_f32_e32 v210, v214, v210
	v_mul_f32_e32 v211, v215, v211
	v_cvt_pk_bf16_f32 v220, v208, v209
	v_cvt_pk_bf16_f32 v221, v210, v211
	global_store_dwordx2 v[222:223], v[220:221], off
	s_ashr_i32 s80, s71, 6
	s_lshl_b32 s80, s80, 2
	s_add_i32 s80, s80, 8
	v_add_u32_e32 v226, s80, v190
	v_mov_b64_e32 v[222:223], s[8:9]
	s_movk_i32 s80, 0x5800
	v_mad_i64_i32 v[222:223], s[78:79], v226, s80, v[222:223]
	v_lshl_add_u64 v[222:223], v[228:229], 2, v[222:223]
	s_and_saveexec_b64 s[76:77], s[42:43]
	global_store_dwordx4 v[222:223], v[8:11], off
	global_store_dwordx4 v[222:223], v[4:7], off offset:16
	s_or_b64 exec, exec, s[76:77]
